# v17 + peeled first iteration takes SrcC=0 on first touch (128 accumulator-zeroing v_mov per unit removed) and the three store-drain vmcnt(0) left in the P5a/P5b/P10 unit preheaders removed
# baseline (speedup 1.0000x reference)
.LBB0_223:
	s_ashr_i32 s23, s22, 31
	s_lshl_b64 s[24:25], s[22:23], 20
	s_add_u32 s24, s81, s24
	s_addc_u32 s25, s85, s25
	s_and_b64 s[26:27], s[2:3], exec
	s_cselect_b32 s5, s25, s29
	s_cselect_b32 s7, s24, s28
	s_ashr_i32 s21, s20, 31
	s_lshl_b64 s[26:27], s[20:21], 20
	s_add_u32 s26, s92, s26
	s_addc_u32 s27, s97, s27
	s_and_b64 s[34:35], s[2:3], exec
	s_cselect_b32 s21, s27, s31
	s_cselect_b32 s23, s26, s30
	s_add_u32 s28, s28, 0x80080
	s_addc_u32 s29, s29, 0
	s_add_u32 s36, s30, 0x100
	s_addc_u32 s37, s31, 0
	s_mov_b32 s38, -2
	ds_read_b128 v[46:49], v196
	ds_read_b128 v[50:53], v196 offset:1024
	ds_read_b128 v[66:69], v196 offset:2048
	ds_read_b128 v[70:73], v196 offset:3072
	ds_read_b128 v[164:167], v197
	ds_read_b128 v[168:171], v197 offset:1024
	ds_read_b128 v[172:175], v197 offset:2048
	ds_read_b128 v[176:179], v197 offset:3072
	s_add_u32 s30, s28, 0xfff80080
	s_addc_u32 s31, s29, -1
	s_cmp_eq_u32 s38, 28
	s_cselect_b32 s35, s5, s31
	s_cselect_b32 s34, s7, s30
	s_cselect_b32 s31, s21, s37
	s_cselect_b32 s30, s23, s36
	s_add_i32 m0, s17, 0xc000
	ds_read_b128 v[184:187], v198
	ds_read_b128 v[188:191], v198 offset:1024
	ds_read_b128 v[200:203], v198 offset:2048
	ds_read_b128 v[204:207], v198 offset:3072
	ds_read_b128 v[208:211], v198 offset:4096
	ds_read_b128 v[212:215], v198 offset:5120
	ds_read_b128 v[216:219], v198 offset:6144
	ds_read_b128 v[220:223], v198 offset:7168
	global_load_lds_dwordx4 v156, s[28:29]
	s_add_i32 m0, s17, 0xe000
	s_nop 0
	global_load_lds_dwordx4 v158, s[28:29]
	s_cmp_lg_u32 s32, 0
	s_cbranch_scc1 .Lpw0a
	s_waitcnt vmcnt(8)
.Lpw0a:
	s_waitcnt lgkmcnt(0)
	s_barrier
	s_setprio 1
	s_waitcnt lgkmcnt(0)
	v_mfma_i32_16x16x64_i8 v[142:145], v[46:49], v[184:187], 0
	v_mfma_i32_16x16x64_i8 v[138:141], v[66:69], v[184:187], 0
	v_mfma_i32_16x16x64_i8 v[134:137], v[46:49], v[200:203], 0
	v_mfma_i32_16x16x64_i8 v[130:133], v[66:69], v[200:203], 0
	v_mfma_i32_16x16x64_i8 v[118:121], v[46:49], v[208:211], 0
	v_mfma_i32_16x16x64_i8 v[114:117], v[66:69], v[208:211], 0
	v_mfma_i32_16x16x64_i8 v[102:105], v[46:49], v[216:219], 0
	v_mfma_i32_16x16x64_i8 v[98:101], v[66:69], v[216:219], 0
	v_mfma_i32_16x16x64_i8 v[142:145], v[50:53], v[188:191], v[142:145]
	v_mfma_i32_16x16x64_i8 v[138:141], v[70:73], v[188:191], v[138:141]
	v_mfma_i32_16x16x64_i8 v[134:137], v[50:53], v[204:207], v[134:137]
	v_mfma_i32_16x16x64_i8 v[130:133], v[70:73], v[204:207], v[130:133]
	v_mfma_i32_16x16x64_i8 v[118:121], v[50:53], v[212:215], v[118:121]
	v_mfma_i32_16x16x64_i8 v[114:117], v[70:73], v[212:215], v[114:117]
	v_mfma_i32_16x16x64_i8 v[102:105], v[50:53], v[220:223], v[102:105]
	v_mfma_i32_16x16x64_i8 v[98:101], v[70:73], v[220:223], v[98:101]
	s_setprio 0
	s_setprio 1
	v_mfma_i32_16x16x64_i8 v[126:129], v[164:167], v[184:187], 0
	v_mfma_i32_16x16x64_i8 v[122:125], v[172:175], v[184:187], 0
	v_mfma_i32_16x16x64_i8 v[110:113], v[164:167], v[200:203], 0
	v_mfma_i32_16x16x64_i8 v[106:109], v[172:175], v[200:203], 0
	v_mfma_i32_16x16x64_i8 v[94:97], v[164:167], v[208:211], 0
	v_mfma_i32_16x16x64_i8 v[90:93], v[172:175], v[208:211], 0
	v_mfma_i32_16x16x64_i8 v[86:89], v[164:167], v[216:219], 0
	v_mfma_i32_16x16x64_i8 v[82:85], v[172:175], v[216:219], 0
	v_mfma_i32_16x16x64_i8 v[126:129], v[168:171], v[188:191], v[126:129]
	v_mfma_i32_16x16x64_i8 v[122:125], v[176:179], v[188:191], v[122:125]
	v_mfma_i32_16x16x64_i8 v[110:113], v[168:171], v[204:207], v[110:113]
	v_mfma_i32_16x16x64_i8 v[106:109], v[176:179], v[204:207], v[106:109]
	v_mfma_i32_16x16x64_i8 v[94:97], v[168:171], v[212:215], v[94:97]
	v_mfma_i32_16x16x64_i8 v[90:93], v[176:179], v[212:215], v[90:93]
	v_mfma_i32_16x16x64_i8 v[86:89], v[168:171], v[220:223], v[86:89]
	v_mfma_i32_16x16x64_i8 v[82:85], v[176:179], v[220:223], v[82:85]
	s_setprio 0
	s_barrier
	s_add_i32 s39, s76, s9
	s_mov_b32 m0, s39
	ds_read_b128 v[184:187], v198 offset:16384
	ds_read_b128 v[188:191], v198 offset:17408
	ds_read_b128 v[200:203], v198 offset:18432
	ds_read_b128 v[204:207], v198 offset:19456
	ds_read_b128 v[208:211], v198 offset:20480
	ds_read_b128 v[212:215], v198 offset:21504
	ds_read_b128 v[216:219], v198 offset:22528
	ds_read_b128 v[220:223], v198 offset:23552
	global_load_lds_dwordx4 v146, s[30:31]
	s_add_i32 m0, s39, 0x2000
	s_add_u32 s46, s30, 0x80000
	s_addc_u32 s47, s31, 0
	s_add_i32 s39, s77, s9
	global_load_lds_dwordx4 v148, s[30:31]
	s_mov_b32 m0, s39
	s_nop 0
	global_load_lds_dwordx4 v146, s[46:47]
	s_add_i32 m0, s39, 0x2000
	s_nop 0
	global_load_lds_dwordx4 v148, s[46:47]
	s_mov_b32 m0, s17
	s_nop 0
	global_load_lds_dwordx4 v146, s[34:35]
	s_mov_b32 m0, s40
	s_nop 0
	global_load_lds_dwordx4 v148, s[34:35]
	s_cmp_lg_u32 s32, 0
	s_cbranch_scc1 .Lpw0b
	s_waitcnt vmcnt(8)
.Lpw0b:
	s_mov_b32 s32, 1
	s_waitcnt lgkmcnt(0)
	s_barrier
	s_setprio 1
	s_waitcnt lgkmcnt(0)
	v_mfma_i32_16x16x64_i8 v[78:81], v[46:49], v[184:187], 0
	v_mfma_i32_16x16x64_i8 v[74:77], v[66:69], v[184:187], 0
	v_mfma_i32_16x16x64_i8 v[54:57], v[46:49], v[200:203], 0
	v_mfma_i32_16x16x64_i8 v[42:45], v[66:69], v[200:203], 0
	v_mfma_i32_16x16x64_i8 v[30:33], v[46:49], v[208:211], 0
	v_mfma_i32_16x16x64_i8 v[26:29], v[66:69], v[208:211], 0
	v_mfma_i32_16x16x64_i8 v[14:17], v[46:49], v[216:219], 0
	v_mfma_i32_16x16x64_i8 v[10:13], v[66:69], v[216:219], 0
	v_mfma_i32_16x16x64_i8 v[78:81], v[50:53], v[188:191], v[78:81]
	v_mfma_i32_16x16x64_i8 v[74:77], v[70:73], v[188:191], v[74:77]
	v_mfma_i32_16x16x64_i8 v[54:57], v[50:53], v[204:207], v[54:57]
	v_mfma_i32_16x16x64_i8 v[42:45], v[70:73], v[204:207], v[42:45]
	v_mfma_i32_16x16x64_i8 v[30:33], v[50:53], v[212:215], v[30:33]
	v_mfma_i32_16x16x64_i8 v[26:29], v[70:73], v[212:215], v[26:29]
	v_mfma_i32_16x16x64_i8 v[14:17], v[50:53], v[220:223], v[14:17]
	v_mfma_i32_16x16x64_i8 v[10:13], v[70:73], v[220:223], v[10:13]
	s_setprio 0
	s_setprio 1
	v_mfma_i32_16x16x64_i8 v[38:41], v[164:167], v[200:203], 0
	v_mfma_i32_16x16x64_i8 v[34:37], v[172:175], v[200:203], 0
	v_mfma_i32_16x16x64_i8 v[22:25], v[164:167], v[208:211], 0
	v_mfma_i32_16x16x64_i8 v[18:21], v[172:175], v[208:211], 0
	v_mfma_i32_16x16x64_i8 v[6:9], v[164:167], v[216:219], 0
	v_mfma_i32_16x16x64_i8 v[2:5], v[172:175], v[216:219], 0
	v_mfma_i32_16x16x64_i8 v[46:49], v[164:167], v[184:187], 0
	v_mfma_i32_16x16x64_i8 v[50:53], v[172:175], v[184:187], 0
	v_mfma_i32_16x16x64_i8 v[38:41], v[168:171], v[204:207], v[38:41]
	v_mfma_i32_16x16x64_i8 v[34:37], v[176:179], v[204:207], v[34:37]
	v_mfma_i32_16x16x64_i8 v[22:25], v[168:171], v[212:215], v[22:25]
	v_mfma_i32_16x16x64_i8 v[18:21], v[176:179], v[212:215], v[18:21]
	v_mfma_i32_16x16x64_i8 v[6:9], v[168:171], v[220:223], v[6:9]
	v_mfma_i32_16x16x64_i8 v[2:5], v[176:179], v[220:223], v[2:5]
	v_mfma_i32_16x16x64_i8 v[46:49], v[168:171], v[188:191], v[46:49]
	v_mfma_i32_16x16x64_i8 v[50:53], v[176:179], v[188:191], v[50:53]
	s_setprio 0
	s_barrier
	s_add_i32 s39, 0, 0x18000
	v_add_u32_e32 v1, s39, v194
	s_add_i32 s46, 0, 0x1c000
	ds_read_b128 v[58:61], v1
	ds_read_b128 v[62:65], v1 offset:1024
	ds_read_b128 v[66:69], v1 offset:2048
	ds_read_b128 v[70:73], v1 offset:3072
	v_add_u32_e32 v1, s46, v194
	ds_read_b128 v[164:167], v1
	ds_read_b128 v[168:171], v1 offset:1024
	ds_read_b128 v[172:175], v1 offset:2048
	ds_read_b128 v[176:179], v1 offset:3072
	s_add_u32 s34, s34, 0x80000
	s_addc_u32 s35, s35, 0
	s_mov_b32 m0, s41
	ds_read_b128 v[184:187], v198 offset:32768
	ds_read_b128 v[188:191], v198 offset:33792
	ds_read_b128 v[200:203], v198 offset:34816
	ds_read_b128 v[204:207], v198 offset:35840
	ds_read_b128 v[208:211], v198 offset:36864
	ds_read_b128 v[212:215], v198 offset:37888
	ds_read_b128 v[216:219], v198 offset:38912
	ds_read_b128 v[220:223], v198 offset:39936
	global_load_lds_dwordx4 v146, s[34:35]
	s_mov_b32 m0, s42
	s_nop 0
	global_load_lds_dwordx4 v148, s[34:35]
	s_waitcnt vmcnt(8)
	s_waitcnt lgkmcnt(0)
	s_barrier
	s_setprio 1
	s_waitcnt lgkmcnt(0)
	v_mfma_i32_16x16x64_i8 v[142:145], v[58:61], v[184:187], v[142:145]
	v_mfma_i32_16x16x64_i8 v[138:141], v[66:69], v[184:187], v[138:141]
	v_mfma_i32_16x16x64_i8 v[134:137], v[58:61], v[200:203], v[134:137]
	v_mfma_i32_16x16x64_i8 v[130:133], v[66:69], v[200:203], v[130:133]
	v_mfma_i32_16x16x64_i8 v[118:121], v[58:61], v[208:211], v[118:121]
	v_mfma_i32_16x16x64_i8 v[114:117], v[66:69], v[208:211], v[114:117]
	v_mfma_i32_16x16x64_i8 v[102:105], v[58:61], v[216:219], v[102:105]
	v_mfma_i32_16x16x64_i8 v[98:101], v[66:69], v[216:219], v[98:101]
	v_mfma_i32_16x16x64_i8 v[142:145], v[62:65], v[188:191], v[142:145]
	v_mfma_i32_16x16x64_i8 v[138:141], v[70:73], v[188:191], v[138:141]
	v_mfma_i32_16x16x64_i8 v[134:137], v[62:65], v[204:207], v[134:137]
	v_mfma_i32_16x16x64_i8 v[130:133], v[70:73], v[204:207], v[130:133]
	v_mfma_i32_16x16x64_i8 v[118:121], v[62:65], v[212:215], v[118:121]
	v_mfma_i32_16x16x64_i8 v[114:117], v[70:73], v[212:215], v[114:117]
	v_mfma_i32_16x16x64_i8 v[102:105], v[62:65], v[220:223], v[102:105]
	v_mfma_i32_16x16x64_i8 v[98:101], v[70:73], v[220:223], v[98:101]
	s_setprio 0
	s_setprio 1
	v_mfma_i32_16x16x64_i8 v[126:129], v[164:167], v[184:187], v[126:129]
	v_mfma_i32_16x16x64_i8 v[122:125], v[172:175], v[184:187], v[122:125]
	v_mfma_i32_16x16x64_i8 v[110:113], v[164:167], v[200:203], v[110:113]
	v_mfma_i32_16x16x64_i8 v[106:109], v[172:175], v[200:203], v[106:109]
	v_mfma_i32_16x16x64_i8 v[94:97], v[164:167], v[208:211], v[94:97]
	v_mfma_i32_16x16x64_i8 v[90:93], v[172:175], v[208:211], v[90:93]
	v_mfma_i32_16x16x64_i8 v[86:89], v[164:167], v[216:219], v[86:89]
	v_mfma_i32_16x16x64_i8 v[82:85], v[172:175], v[216:219], v[82:85]
	v_mfma_i32_16x16x64_i8 v[126:129], v[168:171], v[188:191], v[126:129]
	v_mfma_i32_16x16x64_i8 v[122:125], v[176:179], v[188:191], v[122:125]
	v_mfma_i32_16x16x64_i8 v[110:113], v[168:171], v[204:207], v[110:113]
	v_mfma_i32_16x16x64_i8 v[106:109], v[176:179], v[204:207], v[106:109]
	v_mfma_i32_16x16x64_i8 v[94:97], v[168:171], v[212:215], v[94:97]
	v_mfma_i32_16x16x64_i8 v[90:93], v[176:179], v[212:215], v[90:93]
	v_mfma_i32_16x16x64_i8 v[86:89], v[168:171], v[220:223], v[86:89]
	v_mfma_i32_16x16x64_i8 v[82:85], v[176:179], v[220:223], v[82:85]
	s_setprio 0
	s_barrier
	s_add_u32 s98, s34, 0xfff80080
	s_addc_u32 s99, s35, -1
	s_add_i32 s34, s39, s9
	s_mov_b32 m0, s34
	ds_read_b128 v[184:187], v198 offset:49152
	ds_read_b128 v[188:191], v198 offset:50176
	ds_read_b128 v[200:203], v198 offset:51200
	ds_read_b128 v[204:207], v198 offset:52224
	ds_read_b128 v[208:211], v198 offset:53248
	ds_read_b128 v[212:215], v198 offset:54272
	ds_read_b128 v[216:219], v198 offset:55296
	ds_read_b128 v[220:223], v198 offset:56320
	s_add_u32 s100, s30, 0x80
	s_addc_u32 s101, s31, 0
	global_load_lds_dwordx4 v146, s[100:101]
	s_add_i32 m0, s34, 0x2000
	s_add_u32 s30, s30, 0x80080
	s_addc_u32 s31, s31, 0
	s_add_i32 s34, s46, s9
	global_load_lds_dwordx4 v148, s[100:101]
	s_mov_b32 m0, s34
	s_nop 0
	global_load_lds_dwordx4 v146, s[30:31]
	s_add_i32 m0, s34, 0x2000
	s_nop 0
	global_load_lds_dwordx4 v148, s[30:31]
	s_mov_b32 m0, s72
	s_nop 0
	global_load_lds_dwordx4 v146, s[98:99]
	s_mov_b32 m0, s73
	s_nop 0
	global_load_lds_dwordx4 v148, s[98:99]
	s_waitcnt vmcnt(8)
	s_waitcnt lgkmcnt(0)
	s_barrier
	s_setprio 1
	s_waitcnt lgkmcnt(0)
	v_mfma_i32_16x16x64_i8 v[78:81], v[58:61], v[184:187], v[78:81]
	v_mfma_i32_16x16x64_i8 v[74:77], v[66:69], v[184:187], v[74:77]
	v_mfma_i32_16x16x64_i8 v[54:57], v[58:61], v[200:203], v[54:57]
	v_mfma_i32_16x16x64_i8 v[42:45], v[66:69], v[200:203], v[42:45]
	v_mfma_i32_16x16x64_i8 v[30:33], v[58:61], v[208:211], v[30:33]
	v_mfma_i32_16x16x64_i8 v[26:29], v[66:69], v[208:211], v[26:29]
	v_mfma_i32_16x16x64_i8 v[14:17], v[58:61], v[216:219], v[14:17]
	v_mfma_i32_16x16x64_i8 v[10:13], v[66:69], v[216:219], v[10:13]
	v_mfma_i32_16x16x64_i8 v[78:81], v[62:65], v[188:191], v[78:81]
	v_mfma_i32_16x16x64_i8 v[74:77], v[70:73], v[188:191], v[74:77]
	v_mfma_i32_16x16x64_i8 v[54:57], v[62:65], v[204:207], v[54:57]
	v_mfma_i32_16x16x64_i8 v[42:45], v[70:73], v[204:207], v[42:45]
	v_mfma_i32_16x16x64_i8 v[30:33], v[62:65], v[212:215], v[30:33]
	v_mfma_i32_16x16x64_i8 v[26:29], v[70:73], v[212:215], v[26:29]
	v_mfma_i32_16x16x64_i8 v[14:17], v[62:65], v[220:223], v[14:17]
	v_mfma_i32_16x16x64_i8 v[10:13], v[70:73], v[220:223], v[10:13]
	s_setprio 0
	s_setprio 1
	v_mfma_i32_16x16x64_i8 v[46:49], v[164:167], v[184:187], v[46:49]
	v_mfma_i32_16x16x64_i8 v[62:65], v[168:171], v[188:191], v[46:49]
	v_mfma_i32_16x16x64_i8 v[46:49], v[172:175], v[184:187], v[50:53]
	v_mfma_i32_16x16x64_i8 v[38:41], v[164:167], v[200:203], v[38:41]
	v_mfma_i32_16x16x64_i8 v[34:37], v[172:175], v[200:203], v[34:37]
	v_mfma_i32_16x16x64_i8 v[22:25], v[164:167], v[208:211], v[22:25]
	v_mfma_i32_16x16x64_i8 v[18:21], v[172:175], v[208:211], v[18:21]
	v_mfma_i32_16x16x64_i8 v[6:9], v[164:167], v[216:219], v[6:9]
	v_mfma_i32_16x16x64_i8 v[2:5], v[172:175], v[216:219], v[2:5]
	v_mfma_i32_16x16x64_i8 v[58:61], v[176:179], v[188:191], v[46:49]
	v_mfma_i32_16x16x64_i8 v[38:41], v[168:171], v[204:207], v[38:41]
	v_mfma_i32_16x16x64_i8 v[34:37], v[176:179], v[204:207], v[34:37]
	v_mfma_i32_16x16x64_i8 v[22:25], v[168:171], v[212:215], v[22:25]
	v_mfma_i32_16x16x64_i8 v[18:21], v[176:179], v[212:215], v[18:21]
	v_mfma_i32_16x16x64_i8 v[6:9], v[168:171], v[220:223], v[6:9]
	v_mfma_i32_16x16x64_i8 v[2:5], v[176:179], v[220:223], v[2:5]
	s_setprio 0
	s_barrier
	s_add_i32 s38, s38, 2
	s_add_u32 s28, s28, 0x100
	s_addc_u32 s29, s29, 0
	s_add_u32 s36, s36, 0x100
	s_addc_u32 s37, s37, 0
	s_cmp_gt_u32 s38, 29

.LBB0_549:
	s_ashr_i32 s25, s24, 31
	s_lshl_b64 s[26:27], s[24:25], 19
	s_add_u32 s26, s48, s26
	s_addc_u32 s27, s49, s27
	s_and_b64 s[28:29], s[2:3], exec
	s_cselect_b32 s25, s27, s35
	s_cselect_b32 s70, s26, s34
	s_ashr_i32 s23, s22, 31
	s_lshl_b64 s[28:29], s[22:23], 19
	v_readlane_b32 s72, v254, 10
	s_add_u32 s28, s72, s28
	s_addc_u32 s29, s79, s29
	s_and_b64 s[38:39], s[2:3], exec
	s_cselect_b32 s23, s29, s37
	s_cselect_b32 s71, s28, s36
	s_add_u32 s34, s34, 0x40080
	s_addc_u32 s35, s35, 0
	v_readlane_b32 s73, v254, 11
	v_readlane_b32 s74, v254, 12
	s_add_u32 s72, s36, 0x100
	s_addc_u32 s73, s37, 0
	s_mov_b32 s74, -2
	v_readlane_b32 s75, v254, 13
	ds_read_b128 v[106:109], v147
	ds_read_b128 v[110:113], v147 offset:1024
	ds_read_b128 v[114:117], v147 offset:2048
	ds_read_b128 v[118:121], v147 offset:3072
	ds_read_b128 v[174:177], v197
	ds_read_b128 v[200:203], v197 offset:1024
	ds_read_b128 v[204:207], v197 offset:2048
	ds_read_b128 v[208:211], v197 offset:3072
	s_add_u32 s36, s34, 0xfffc0080
	s_addc_u32 s37, s35, -1
	s_cmp_eq_u32 s74, 12
	s_cselect_b32 s39, s25, s37
	s_cselect_b32 s38, s70, s36
	s_cselect_b32 s37, s23, s73
	s_cselect_b32 s36, s71, s72
	s_add_i32 m0, s31, 0xc000
	ds_read_b128 v[212:215], v198
	ds_read_b128 v[216:219], v198 offset:1024
	ds_read_b128 v[220:223], v198 offset:2048
	ds_read_b128 v[224:227], v198 offset:3072
	ds_read_b128 v[228:231], v198 offset:4096
	ds_read_b128 v[232:235], v198 offset:5120
	ds_read_b128 v[236:239], v198 offset:6144
	ds_read_b128 v[240:243], v198 offset:7168
	global_load_lds_dwordx4 v154, s[34:35]
	s_add_i32 m0, s31, 0xe000
	s_nop 0
	global_load_lds_dwordx4 v156, s[34:35]
	s_cmp_lg_u32 s32, 0
	s_cbranch_scc1 .Lpw1a
	s_waitcnt vmcnt(8)
.Lpw1a:
	s_waitcnt lgkmcnt(0)
	s_barrier
	s_setprio 1
	s_waitcnt lgkmcnt(0)
	v_mfma_i32_16x16x64_i8 v[142:145], v[106:109], v[212:215], 0
	v_mfma_i32_16x16x64_i8 v[138:141], v[114:117], v[212:215], 0
	v_mfma_i32_16x16x64_i8 v[126:129], v[106:109], v[220:223], 0
	v_mfma_i32_16x16x64_i8 v[122:125], v[114:117], v[220:223], 0
	v_mfma_i32_16x16x64_i8 v[94:97], v[106:109], v[228:231], 0
	v_mfma_i32_16x16x64_i8 v[90:93], v[114:117], v[228:231], 0
	v_mfma_i32_16x16x64_i8 v[78:81], v[106:109], v[236:239], 0
	v_mfma_i32_16x16x64_i8 v[74:77], v[114:117], v[236:239], 0
	v_mfma_i32_16x16x64_i8 v[142:145], v[110:113], v[216:219], v[142:145]
	v_mfma_i32_16x16x64_i8 v[138:141], v[118:121], v[216:219], v[138:141]
	v_mfma_i32_16x16x64_i8 v[126:129], v[110:113], v[224:227], v[126:129]
	v_mfma_i32_16x16x64_i8 v[122:125], v[118:121], v[224:227], v[122:125]
	v_mfma_i32_16x16x64_i8 v[94:97], v[110:113], v[232:235], v[94:97]
	v_mfma_i32_16x16x64_i8 v[90:93], v[118:121], v[232:235], v[90:93]
	v_mfma_i32_16x16x64_i8 v[78:81], v[110:113], v[240:243], v[78:81]
	v_mfma_i32_16x16x64_i8 v[74:77], v[118:121], v[240:243], v[74:77]
	s_setprio 0
	s_setprio 1
	v_mfma_i32_16x16x64_i8 v[134:137], v[174:177], v[212:215], 0
	v_mfma_i32_16x16x64_i8 v[130:133], v[204:207], v[212:215], 0
	v_mfma_i32_16x16x64_i8 v[102:105], v[174:177], v[220:223], 0
	v_mfma_i32_16x16x64_i8 v[98:101], v[204:207], v[220:223], 0
	v_mfma_i32_16x16x64_i8 v[86:89], v[174:177], v[228:231], 0
	v_mfma_i32_16x16x64_i8 v[82:85], v[204:207], v[228:231], 0
	v_mfma_i32_16x16x64_i8 v[70:73], v[174:177], v[236:239], 0
	v_mfma_i32_16x16x64_i8 v[66:69], v[204:207], v[236:239], 0
	v_mfma_i32_16x16x64_i8 v[134:137], v[200:203], v[216:219], v[134:137]
	v_mfma_i32_16x16x64_i8 v[130:133], v[208:211], v[216:219], v[130:133]
	v_mfma_i32_16x16x64_i8 v[102:105], v[200:203], v[224:227], v[102:105]
	v_mfma_i32_16x16x64_i8 v[98:101], v[208:211], v[224:227], v[98:101]
	v_mfma_i32_16x16x64_i8 v[86:89], v[200:203], v[232:235], v[86:89]
	v_mfma_i32_16x16x64_i8 v[82:85], v[208:211], v[232:235], v[82:85]
	v_mfma_i32_16x16x64_i8 v[70:73], v[200:203], v[240:243], v[70:73]
	v_mfma_i32_16x16x64_i8 v[66:69], v[208:211], v[240:243], v[66:69]
	s_setprio 0
	s_barrier
	s_add_i32 s75, s67, s41
	s_mov_b32 m0, s75
	ds_read_b128 v[212:215], v198 offset:16384
	ds_read_b128 v[216:219], v198 offset:17408
	ds_read_b128 v[220:223], v198 offset:18432
	ds_read_b128 v[224:227], v198 offset:19456
	ds_read_b128 v[228:231], v198 offset:20480
	ds_read_b128 v[232:235], v198 offset:21504
	ds_read_b128 v[236:239], v198 offset:22528
	ds_read_b128 v[240:243], v198 offset:23552
	global_load_lds_dwordx4 v148, s[36:37]
	s_add_i32 m0, s75, 0x2000
	s_add_u32 s76, s36, 0x40000
	s_addc_u32 s77, s37, 0
	s_add_i32 s75, s68, s41
	global_load_lds_dwordx4 v150, s[36:37]
	s_mov_b32 m0, s75
	s_nop 0
	global_load_lds_dwordx4 v148, s[76:77]
	s_add_i32 m0, s75, 0x2000
	s_nop 0
	global_load_lds_dwordx4 v150, s[76:77]
	s_mov_b32 m0, s31
	s_nop 0
	global_load_lds_dwordx4 v148, s[38:39]
	s_mov_b32 m0, s42
	s_nop 0
	global_load_lds_dwordx4 v150, s[38:39]
	s_cmp_lg_u32 s32, 0
	s_cbranch_scc1 .Lpw1b
	s_waitcnt vmcnt(8)
.Lpw1b:
	s_mov_b32 s32, 1
	s_waitcnt lgkmcnt(0)
	s_barrier
	s_setprio 1
	s_waitcnt lgkmcnt(0)
	v_mfma_i32_16x16x64_i8 v[62:65], v[106:109], v[212:215], 0
	v_mfma_i32_16x16x64_i8 v[58:61], v[114:117], v[212:215], 0
	v_mfma_i32_16x16x64_i8 v[46:49], v[106:109], v[220:223], 0
	v_mfma_i32_16x16x64_i8 v[42:45], v[114:117], v[220:223], 0
	v_mfma_i32_16x16x64_i8 v[30:33], v[106:109], v[228:231], 0
	v_mfma_i32_16x16x64_i8 v[26:29], v[114:117], v[228:231], 0
	v_mfma_i32_16x16x64_i8 v[14:17], v[106:109], v[236:239], 0
	v_mfma_i32_16x16x64_i8 v[10:13], v[114:117], v[236:239], 0
	v_mfma_i32_16x16x64_i8 v[62:65], v[110:113], v[216:219], v[62:65]
	v_mfma_i32_16x16x64_i8 v[58:61], v[118:121], v[216:219], v[58:61]
	v_mfma_i32_16x16x64_i8 v[46:49], v[110:113], v[224:227], v[46:49]
	v_mfma_i32_16x16x64_i8 v[42:45], v[118:121], v[224:227], v[42:45]
	v_mfma_i32_16x16x64_i8 v[30:33], v[110:113], v[232:235], v[30:33]
	v_mfma_i32_16x16x64_i8 v[26:29], v[118:121], v[232:235], v[26:29]
	v_mfma_i32_16x16x64_i8 v[14:17], v[110:113], v[240:243], v[14:17]
	v_mfma_i32_16x16x64_i8 v[10:13], v[118:121], v[240:243], v[10:13]
	s_setprio 0
	s_setprio 1
	v_mfma_i32_16x16x64_i8 v[54:57], v[174:177], v[212:215], 0
	v_mfma_i32_16x16x64_i8 v[50:53], v[204:207], v[212:215], 0
	v_mfma_i32_16x16x64_i8 v[38:41], v[174:177], v[220:223], 0
	v_mfma_i32_16x16x64_i8 v[34:37], v[204:207], v[220:223], 0
	v_mfma_i32_16x16x64_i8 v[22:25], v[174:177], v[228:231], 0
	v_mfma_i32_16x16x64_i8 v[18:21], v[204:207], v[228:231], 0
	v_mfma_i32_16x16x64_i8 v[6:9], v[174:177], v[236:239], 0
	v_mfma_i32_16x16x64_i8 v[2:5], v[204:207], v[236:239], 0
	v_mfma_i32_16x16x64_i8 v[54:57], v[200:203], v[216:219], v[54:57]
	v_mfma_i32_16x16x64_i8 v[50:53], v[208:211], v[216:219], v[50:53]
	v_mfma_i32_16x16x64_i8 v[38:41], v[200:203], v[224:227], v[38:41]
	v_mfma_i32_16x16x64_i8 v[34:37], v[208:211], v[224:227], v[34:37]
	v_mfma_i32_16x16x64_i8 v[22:25], v[200:203], v[232:235], v[22:25]
	v_mfma_i32_16x16x64_i8 v[18:21], v[208:211], v[232:235], v[18:21]
	v_mfma_i32_16x16x64_i8 v[6:9], v[200:203], v[240:243], v[6:9]
	v_mfma_i32_16x16x64_i8 v[2:5], v[208:211], v[240:243], v[2:5]
	s_setprio 0
	s_barrier
	s_add_i32 s75, 0, 0x18000
	s_add_i32 s76, 0, 0x1c000
	v_add_u32_e32 v118, s75, v195
	v_add_u32_e32 v164, s76, v195
	ds_read_b128 v[106:109], v118
	ds_read_b128 v[110:113], v118 offset:1024
	ds_read_b128 v[114:117], v118 offset:2048
	ds_read_b128 v[118:121], v118 offset:3072
	ds_read_b128 v[174:177], v164
	ds_read_b128 v[200:203], v164 offset:1024
	ds_read_b128 v[204:207], v164 offset:2048
	ds_read_b128 v[208:211], v164 offset:3072
	s_add_u32 s38, s38, 0x40000
	s_addc_u32 s39, s39, 0
	s_mov_b32 m0, s43
	ds_read_b128 v[212:215], v198 offset:32768
	ds_read_b128 v[216:219], v198 offset:33792
	ds_read_b128 v[220:223], v198 offset:34816
	ds_read_b128 v[224:227], v198 offset:35840
	ds_read_b128 v[228:231], v198 offset:36864
	ds_read_b128 v[232:235], v198 offset:37888
	ds_read_b128 v[236:239], v198 offset:38912
	ds_read_b128 v[240:243], v198 offset:39936
	global_load_lds_dwordx4 v148, s[38:39]
	s_mov_b32 m0, s46
	s_nop 0
	global_load_lds_dwordx4 v150, s[38:39]
	s_waitcnt vmcnt(8)
	s_waitcnt lgkmcnt(0)
	s_barrier
	s_setprio 1
	s_waitcnt lgkmcnt(0)
	v_mfma_i32_16x16x64_i8 v[142:145], v[106:109], v[212:215], v[142:145]
	v_mfma_i32_16x16x64_i8 v[138:141], v[114:117], v[212:215], v[138:141]
	v_mfma_i32_16x16x64_i8 v[126:129], v[106:109], v[220:223], v[126:129]
	v_mfma_i32_16x16x64_i8 v[122:125], v[114:117], v[220:223], v[122:125]
	v_mfma_i32_16x16x64_i8 v[94:97], v[106:109], v[228:231], v[94:97]
	v_mfma_i32_16x16x64_i8 v[90:93], v[114:117], v[228:231], v[90:93]
	v_mfma_i32_16x16x64_i8 v[78:81], v[106:109], v[236:239], v[78:81]
	v_mfma_i32_16x16x64_i8 v[74:77], v[114:117], v[236:239], v[74:77]
	v_mfma_i32_16x16x64_i8 v[142:145], v[110:113], v[216:219], v[142:145]
	v_mfma_i32_16x16x64_i8 v[138:141], v[118:121], v[216:219], v[138:141]
	v_mfma_i32_16x16x64_i8 v[126:129], v[110:113], v[224:227], v[126:129]
	v_mfma_i32_16x16x64_i8 v[122:125], v[118:121], v[224:227], v[122:125]
	v_mfma_i32_16x16x64_i8 v[94:97], v[110:113], v[232:235], v[94:97]
	v_mfma_i32_16x16x64_i8 v[90:93], v[118:121], v[232:235], v[90:93]
	v_mfma_i32_16x16x64_i8 v[78:81], v[110:113], v[240:243], v[78:81]
	v_mfma_i32_16x16x64_i8 v[74:77], v[118:121], v[240:243], v[74:77]
	s_setprio 0
	s_setprio 1
	v_mfma_i32_16x16x64_i8 v[134:137], v[174:177], v[212:215], v[134:137]
	v_mfma_i32_16x16x64_i8 v[130:133], v[204:207], v[212:215], v[130:133]
	v_mfma_i32_16x16x64_i8 v[102:105], v[174:177], v[220:223], v[102:105]
	v_mfma_i32_16x16x64_i8 v[98:101], v[204:207], v[220:223], v[98:101]
	v_mfma_i32_16x16x64_i8 v[86:89], v[174:177], v[228:231], v[86:89]
	v_mfma_i32_16x16x64_i8 v[82:85], v[204:207], v[228:231], v[82:85]
	v_mfma_i32_16x16x64_i8 v[70:73], v[174:177], v[236:239], v[70:73]
	v_mfma_i32_16x16x64_i8 v[66:69], v[204:207], v[236:239], v[66:69]
	v_mfma_i32_16x16x64_i8 v[134:137], v[200:203], v[216:219], v[134:137]
	v_mfma_i32_16x16x64_i8 v[130:133], v[208:211], v[216:219], v[130:133]
	v_mfma_i32_16x16x64_i8 v[102:105], v[200:203], v[224:227], v[102:105]
	v_mfma_i32_16x16x64_i8 v[98:101], v[208:211], v[224:227], v[98:101]
	v_mfma_i32_16x16x64_i8 v[86:89], v[200:203], v[232:235], v[86:89]
	v_mfma_i32_16x16x64_i8 v[82:85], v[208:211], v[232:235], v[82:85]
	v_mfma_i32_16x16x64_i8 v[70:73], v[200:203], v[240:243], v[70:73]
	v_mfma_i32_16x16x64_i8 v[66:69], v[208:211], v[240:243], v[66:69]
	s_setprio 0
	s_barrier
	s_add_u32 s98, s38, 0xfffc0080
	s_addc_u32 s99, s39, -1
	s_add_i32 s38, s75, s41
	s_mov_b32 m0, s38
	ds_read_b128 v[212:215], v198 offset:49152
	ds_read_b128 v[216:219], v198 offset:50176
	ds_read_b128 v[220:223], v198 offset:51200
	ds_read_b128 v[224:227], v198 offset:52224
	ds_read_b128 v[228:231], v198 offset:53248
	ds_read_b128 v[232:235], v198 offset:54272
	ds_read_b128 v[236:239], v198 offset:55296
	ds_read_b128 v[240:243], v198 offset:56320
	s_add_u32 s100, s36, 0x80
	s_addc_u32 s101, s37, 0
	global_load_lds_dwordx4 v148, s[100:101]
	s_add_i32 m0, s38, 0x2000
	s_add_u32 s36, s36, 0x40080
	s_addc_u32 s37, s37, 0
	s_add_i32 s38, s76, s41
	global_load_lds_dwordx4 v150, s[100:101]
	s_mov_b32 m0, s38
	s_nop 0
	global_load_lds_dwordx4 v148, s[36:37]
	s_add_i32 m0, s38, 0x2000
	s_nop 0
	global_load_lds_dwordx4 v150, s[36:37]
	s_mov_b32 m0, s56
	s_nop 0
	global_load_lds_dwordx4 v148, s[98:99]
	s_mov_b32 m0, s57
	s_nop 0
	global_load_lds_dwordx4 v150, s[98:99]
	s_waitcnt vmcnt(8)
	s_waitcnt lgkmcnt(0)
	s_barrier
	s_setprio 1
	s_waitcnt lgkmcnt(0)
	v_mfma_i32_16x16x64_i8 v[62:65], v[106:109], v[212:215], v[62:65]
	v_mfma_i32_16x16x64_i8 v[58:61], v[114:117], v[212:215], v[58:61]
	v_mfma_i32_16x16x64_i8 v[46:49], v[106:109], v[220:223], v[46:49]
	v_mfma_i32_16x16x64_i8 v[42:45], v[114:117], v[220:223], v[42:45]
	v_mfma_i32_16x16x64_i8 v[30:33], v[106:109], v[228:231], v[30:33]
	v_mfma_i32_16x16x64_i8 v[26:29], v[114:117], v[228:231], v[26:29]
	v_mfma_i32_16x16x64_i8 v[14:17], v[106:109], v[236:239], v[14:17]
	v_mfma_i32_16x16x64_i8 v[10:13], v[114:117], v[236:239], v[10:13]
	v_mfma_i32_16x16x64_i8 v[62:65], v[110:113], v[216:219], v[62:65]
	v_mfma_i32_16x16x64_i8 v[58:61], v[118:121], v[216:219], v[58:61]
	v_mfma_i32_16x16x64_i8 v[46:49], v[110:113], v[224:227], v[46:49]
	v_mfma_i32_16x16x64_i8 v[42:45], v[118:121], v[224:227], v[42:45]
	v_mfma_i32_16x16x64_i8 v[30:33], v[110:113], v[232:235], v[30:33]
	v_mfma_i32_16x16x64_i8 v[26:29], v[118:121], v[232:235], v[26:29]
	v_mfma_i32_16x16x64_i8 v[14:17], v[110:113], v[240:243], v[14:17]
	v_mfma_i32_16x16x64_i8 v[10:13], v[118:121], v[240:243], v[10:13]
	s_setprio 0
	s_setprio 1
	v_mfma_i32_16x16x64_i8 v[54:57], v[174:177], v[212:215], v[54:57]
	v_mfma_i32_16x16x64_i8 v[50:53], v[204:207], v[212:215], v[50:53]
	v_mfma_i32_16x16x64_i8 v[38:41], v[174:177], v[220:223], v[38:41]
	v_mfma_i32_16x16x64_i8 v[34:37], v[204:207], v[220:223], v[34:37]
	v_mfma_i32_16x16x64_i8 v[22:25], v[174:177], v[228:231], v[22:25]
	v_mfma_i32_16x16x64_i8 v[18:21], v[204:207], v[228:231], v[18:21]
	v_mfma_i32_16x16x64_i8 v[6:9], v[174:177], v[236:239], v[6:9]
	v_mfma_i32_16x16x64_i8 v[2:5], v[204:207], v[236:239], v[2:5]
	v_mfma_i32_16x16x64_i8 v[54:57], v[200:203], v[216:219], v[54:57]
	v_mfma_i32_16x16x64_i8 v[50:53], v[208:211], v[216:219], v[50:53]
	v_mfma_i32_16x16x64_i8 v[38:41], v[200:203], v[224:227], v[38:41]
	v_mfma_i32_16x16x64_i8 v[34:37], v[208:211], v[224:227], v[34:37]
	v_mfma_i32_16x16x64_i8 v[22:25], v[200:203], v[232:235], v[22:25]
	v_mfma_i32_16x16x64_i8 v[18:21], v[208:211], v[232:235], v[18:21]
	v_mfma_i32_16x16x64_i8 v[6:9], v[200:203], v[240:243], v[6:9]
	v_mfma_i32_16x16x64_i8 v[2:5], v[208:211], v[240:243], v[2:5]
	s_setprio 0
	s_barrier
	s_add_i32 s74, s74, 2
	s_add_u32 s34, s34, 0x100
	s_addc_u32 s35, s35, 0
	s_add_u32 s72, s72, 0x100
	s_addc_u32 s73, s73, 0
	s_cmp_gt_u32 s74, 13

.LBB0_573:
	s_ashr_i32 s13, s12, 31
	s_lshl_b64 s[14:15], s[12:13], 18
	s_add_u32 s14, s30, s14
	s_addc_u32 s15, s31, s15
	s_and_b64 s[16:17], s[2:3], exec
	s_cselect_b32 s13, s15, s23
	s_cselect_b32 s46, s14, s22
	s_ashr_i32 s11, s10, 31
	s_lshl_b64 s[16:17], s[10:11], 18
	v_readlane_b32 s68, v254, 4
	s_add_u32 s16, s68, s16
	s_addc_u32 s17, s78, s17
	s_and_b64 s[26:27], s[2:3], exec
	s_cselect_b32 s11, s17, s25
	s_cselect_b32 s47, s16, s24
	s_add_u32 s22, s22, 0x20080
	s_addc_u32 s23, s23, 0
	s_add_u32 s56, s24, 0x100
	s_addc_u32 s57, s25, 0
	s_mov_b32 s66, -2
	v_readlane_b32 s69, v254, 5
	v_readlane_b32 s70, v254, 6
	v_readlane_b32 s71, v254, 7
	ds_read_b128 v[90:93], v1
	ds_read_b128 v[98:101], v1 offset:1024
	ds_read_b128 v[102:105], v1 offset:2048
	ds_read_b128 v[142:145], v1 offset:3072
	ds_read_b128 v[146:149], v203
	ds_read_b128 v[150:153], v203 offset:1024
	ds_read_b128 v[154:157], v203 offset:2048
	ds_read_b128 v[158:161], v203 offset:3072
	s_add_u32 s24, s22, 0xfffe0080
	s_addc_u32 s25, s23, -1
	s_cmp_eq_u32 s66, 4
	s_cselect_b32 s27, s13, s25
	s_cselect_b32 s26, s46, s24
	s_cselect_b32 s25, s11, s57
	s_cselect_b32 s24, s47, s56
	s_add_i32 m0, s19, 0xc000
	ds_read_b128 v[162:165], v205
	ds_read_b128 v[166:169], v205 offset:1024
	ds_read_b128 v[170:173], v205 offset:2048
	ds_read_b128 v[174:177], v205 offset:3072
	ds_read_b128 v[178:181], v205 offset:4096
	ds_read_b128 v[206:209], v205 offset:5120
	ds_read_b128 v[210:213], v205 offset:6144
	ds_read_b128 v[214:217], v205 offset:7168
	global_load_lds_dwordx4 v190, s[22:23]
	s_add_i32 m0, s19, 0xe000
	s_nop 0
	global_load_lds_dwordx4 v192, s[22:23]
	s_cmp_lg_u32 s32, 0
	s_cbranch_scc1 .Lpw2a
	s_waitcnt vmcnt(8)
.Lpw2a:
	s_waitcnt lgkmcnt(0)
	s_barrier
	s_setprio 1
	s_waitcnt lgkmcnt(0)
	v_mfma_i32_16x16x64_i8 v[94:97], v[90:93], v[162:165], 0
	v_mfma_i32_16x16x64_i8 v[138:141], v[102:105], v[162:165], 0
	v_mfma_i32_16x16x64_i8 v[126:129], v[90:93], v[170:173], 0
	v_mfma_i32_16x16x64_i8 v[122:125], v[102:105], v[170:173], 0
	v_mfma_i32_16x16x64_i8 v[110:113], v[90:93], v[178:181], 0
	v_mfma_i32_16x16x64_i8 v[106:109], v[102:105], v[178:181], 0
	v_mfma_i32_16x16x64_i8 v[78:81], v[90:93], v[210:213], 0
	v_mfma_i32_16x16x64_i8 v[74:77], v[102:105], v[210:213], 0
	v_mfma_i32_16x16x64_i8 v[94:97], v[98:101], v[166:169], v[94:97]
	v_mfma_i32_16x16x64_i8 v[138:141], v[142:145], v[166:169], v[138:141]
	v_mfma_i32_16x16x64_i8 v[126:129], v[98:101], v[174:177], v[126:129]
	v_mfma_i32_16x16x64_i8 v[122:125], v[142:145], v[174:177], v[122:125]
	v_mfma_i32_16x16x64_i8 v[110:113], v[98:101], v[206:209], v[110:113]
	v_mfma_i32_16x16x64_i8 v[106:109], v[142:145], v[206:209], v[106:109]
	v_mfma_i32_16x16x64_i8 v[78:81], v[98:101], v[214:217], v[78:81]
	v_mfma_i32_16x16x64_i8 v[74:77], v[142:145], v[214:217], v[74:77]
	s_setprio 0
	s_setprio 1
	v_mfma_i32_16x16x64_i8 v[134:137], v[146:149], v[162:165], 0
	v_mfma_i32_16x16x64_i8 v[130:133], v[154:157], v[162:165], 0
	v_mfma_i32_16x16x64_i8 v[118:121], v[146:149], v[170:173], 0
	v_mfma_i32_16x16x64_i8 v[114:117], v[154:157], v[170:173], 0
	v_mfma_i32_16x16x64_i8 v[86:89], v[146:149], v[178:181], 0
	v_mfma_i32_16x16x64_i8 v[82:85], v[154:157], v[178:181], 0
	v_mfma_i32_16x16x64_i8 v[70:73], v[146:149], v[210:213], 0
	v_mfma_i32_16x16x64_i8 v[66:69], v[154:157], v[210:213], 0
	v_mfma_i32_16x16x64_i8 v[134:137], v[150:153], v[166:169], v[134:137]
	v_mfma_i32_16x16x64_i8 v[130:133], v[158:161], v[166:169], v[130:133]
	v_mfma_i32_16x16x64_i8 v[118:121], v[150:153], v[174:177], v[118:121]
	v_mfma_i32_16x16x64_i8 v[114:117], v[158:161], v[174:177], v[114:117]
	v_mfma_i32_16x16x64_i8 v[86:89], v[150:153], v[206:209], v[86:89]
	v_mfma_i32_16x16x64_i8 v[82:85], v[158:161], v[206:209], v[82:85]
	v_mfma_i32_16x16x64_i8 v[70:73], v[150:153], v[214:217], v[70:73]
	v_mfma_i32_16x16x64_i8 v[66:69], v[158:161], v[214:217], v[66:69]
	s_setprio 0
	s_barrier
	s_add_i32 s67, s41, s29
	s_mov_b32 m0, s67
	ds_read_b128 v[162:165], v205 offset:16384
	ds_read_b128 v[166:169], v205 offset:17408
	ds_read_b128 v[170:173], v205 offset:18432
	ds_read_b128 v[174:177], v205 offset:19456
	ds_read_b128 v[178:181], v205 offset:20480
	ds_read_b128 v[206:209], v205 offset:21504
	ds_read_b128 v[210:213], v205 offset:22528
	ds_read_b128 v[214:217], v205 offset:23552
	global_load_lds_dwordx4 v184, s[24:25]
	s_add_i32 m0, s67, 0x2000
	s_add_u32 s68, s24, 0x20000
	s_addc_u32 s69, s25, 0
	s_add_i32 s67, s42, s29
	global_load_lds_dwordx4 v186, s[24:25]
	s_mov_b32 m0, s67
	s_nop 0
	global_load_lds_dwordx4 v184, s[68:69]
	s_add_i32 m0, s67, 0x2000
	s_nop 0
	global_load_lds_dwordx4 v186, s[68:69]
	s_mov_b32 m0, s19
	s_nop 0
	global_load_lds_dwordx4 v184, s[26:27]
	s_mov_b32 m0, s34
	s_nop 0
	global_load_lds_dwordx4 v186, s[26:27]
	s_cmp_lg_u32 s32, 0
	s_cbranch_scc1 .Lpw2b
	s_waitcnt vmcnt(8)
.Lpw2b:
	s_mov_b32 s32, 1
	s_waitcnt lgkmcnt(0)
	s_barrier
	s_setprio 1
	s_waitcnt lgkmcnt(0)
	v_mfma_i32_16x16x64_i8 v[62:65], v[90:93], v[162:165], 0
	v_mfma_i32_16x16x64_i8 v[58:61], v[102:105], v[162:165], 0
	v_mfma_i32_16x16x64_i8 v[46:49], v[90:93], v[170:173], 0
	v_mfma_i32_16x16x64_i8 v[42:45], v[102:105], v[170:173], 0
	v_mfma_i32_16x16x64_i8 v[30:33], v[90:93], v[178:181], 0
	v_mfma_i32_16x16x64_i8 v[26:29], v[102:105], v[178:181], 0
	v_mfma_i32_16x16x64_i8 v[14:17], v[90:93], v[210:213], 0
	v_mfma_i32_16x16x64_i8 v[10:13], v[102:105], v[210:213], 0
	v_mfma_i32_16x16x64_i8 v[62:65], v[98:101], v[166:169], v[62:65]
	v_mfma_i32_16x16x64_i8 v[58:61], v[142:145], v[166:169], v[58:61]
	v_mfma_i32_16x16x64_i8 v[46:49], v[98:101], v[174:177], v[46:49]
	v_mfma_i32_16x16x64_i8 v[42:45], v[142:145], v[174:177], v[42:45]
	v_mfma_i32_16x16x64_i8 v[30:33], v[98:101], v[206:209], v[30:33]
	v_mfma_i32_16x16x64_i8 v[26:29], v[142:145], v[206:209], v[26:29]
	v_mfma_i32_16x16x64_i8 v[14:17], v[98:101], v[214:217], v[14:17]
	v_mfma_i32_16x16x64_i8 v[10:13], v[142:145], v[214:217], v[10:13]
	s_setprio 0
	s_setprio 1
	v_mfma_i32_16x16x64_i8 v[54:57], v[146:149], v[162:165], 0
	v_mfma_i32_16x16x64_i8 v[50:53], v[154:157], v[162:165], 0
	v_mfma_i32_16x16x64_i8 v[38:41], v[146:149], v[170:173], 0
	v_mfma_i32_16x16x64_i8 v[34:37], v[154:157], v[170:173], 0
	v_mfma_i32_16x16x64_i8 v[22:25], v[146:149], v[178:181], 0
	v_mfma_i32_16x16x64_i8 v[18:21], v[154:157], v[178:181], 0
	v_mfma_i32_16x16x64_i8 v[6:9], v[146:149], v[210:213], 0
	v_mfma_i32_16x16x64_i8 v[2:5], v[154:157], v[210:213], 0
	v_mfma_i32_16x16x64_i8 v[54:57], v[150:153], v[166:169], v[54:57]
	v_mfma_i32_16x16x64_i8 v[50:53], v[158:161], v[166:169], v[50:53]
	v_mfma_i32_16x16x64_i8 v[38:41], v[150:153], v[174:177], v[38:41]
	v_mfma_i32_16x16x64_i8 v[34:37], v[158:161], v[174:177], v[34:37]
	v_mfma_i32_16x16x64_i8 v[22:25], v[150:153], v[206:209], v[22:25]
	v_mfma_i32_16x16x64_i8 v[18:21], v[158:161], v[206:209], v[18:21]
	v_mfma_i32_16x16x64_i8 v[6:9], v[150:153], v[214:217], v[6:9]
	v_mfma_i32_16x16x64_i8 v[2:5], v[158:161], v[214:217], v[2:5]
	s_setprio 0
	s_barrier
	s_add_i32 s67, 0, 0x18000
	s_add_i32 s68, 0, 0x1c000
	v_add_u32_e32 v142, s67, v183
	v_add_u32_e32 v158, s68, v183
	ds_read_b128 v[90:93], v142
	ds_read_b128 v[98:101], v142 offset:1024
	ds_read_b128 v[102:105], v142 offset:2048
	ds_read_b128 v[142:145], v142 offset:3072
	ds_read_b128 v[146:149], v158
	ds_read_b128 v[150:153], v158 offset:1024
	ds_read_b128 v[154:157], v158 offset:2048
	ds_read_b128 v[158:161], v158 offset:3072
	s_add_u32 s26, s26, 0x20000
	s_addc_u32 s27, s27, 0
	s_mov_b32 m0, s35
	ds_read_b128 v[162:165], v205 offset:32768
	ds_read_b128 v[166:169], v205 offset:33792
	ds_read_b128 v[170:173], v205 offset:34816
	ds_read_b128 v[174:177], v205 offset:35840
	ds_read_b128 v[178:181], v205 offset:36864
	ds_read_b128 v[206:209], v205 offset:37888
	ds_read_b128 v[210:213], v205 offset:38912
	ds_read_b128 v[214:217], v205 offset:39936
	global_load_lds_dwordx4 v184, s[26:27]
	s_mov_b32 m0, s36
	s_nop 0
	global_load_lds_dwordx4 v186, s[26:27]
	s_waitcnt vmcnt(8)
	s_waitcnt lgkmcnt(0)
	s_barrier
	s_setprio 1
	s_waitcnt lgkmcnt(0)
	v_mfma_i32_16x16x64_i8 v[94:97], v[90:93], v[162:165], v[94:97]
	v_mfma_i32_16x16x64_i8 v[138:141], v[102:105], v[162:165], v[138:141]
	v_mfma_i32_16x16x64_i8 v[126:129], v[90:93], v[170:173], v[126:129]
	v_mfma_i32_16x16x64_i8 v[122:125], v[102:105], v[170:173], v[122:125]
	v_mfma_i32_16x16x64_i8 v[110:113], v[90:93], v[178:181], v[110:113]
	v_mfma_i32_16x16x64_i8 v[106:109], v[102:105], v[178:181], v[106:109]
	v_mfma_i32_16x16x64_i8 v[78:81], v[90:93], v[210:213], v[78:81]
	v_mfma_i32_16x16x64_i8 v[74:77], v[102:105], v[210:213], v[74:77]
	v_mfma_i32_16x16x64_i8 v[94:97], v[98:101], v[166:169], v[94:97]
	v_mfma_i32_16x16x64_i8 v[138:141], v[142:145], v[166:169], v[138:141]
	v_mfma_i32_16x16x64_i8 v[126:129], v[98:101], v[174:177], v[126:129]
	v_mfma_i32_16x16x64_i8 v[122:125], v[142:145], v[174:177], v[122:125]
	v_mfma_i32_16x16x64_i8 v[110:113], v[98:101], v[206:209], v[110:113]
	v_mfma_i32_16x16x64_i8 v[106:109], v[142:145], v[206:209], v[106:109]
	v_mfma_i32_16x16x64_i8 v[78:81], v[98:101], v[214:217], v[78:81]
	v_mfma_i32_16x16x64_i8 v[74:77], v[142:145], v[214:217], v[74:77]
	s_setprio 0
	s_setprio 1
	v_mfma_i32_16x16x64_i8 v[134:137], v[146:149], v[162:165], v[134:137]
	v_mfma_i32_16x16x64_i8 v[130:133], v[154:157], v[162:165], v[130:133]
	v_mfma_i32_16x16x64_i8 v[118:121], v[146:149], v[170:173], v[118:121]
	v_mfma_i32_16x16x64_i8 v[114:117], v[154:157], v[170:173], v[114:117]
	v_mfma_i32_16x16x64_i8 v[86:89], v[146:149], v[178:181], v[86:89]
	v_mfma_i32_16x16x64_i8 v[82:85], v[154:157], v[178:181], v[82:85]
	v_mfma_i32_16x16x64_i8 v[70:73], v[146:149], v[210:213], v[70:73]
	v_mfma_i32_16x16x64_i8 v[66:69], v[154:157], v[210:213], v[66:69]
	v_mfma_i32_16x16x64_i8 v[134:137], v[150:153], v[166:169], v[134:137]
	v_mfma_i32_16x16x64_i8 v[130:133], v[158:161], v[166:169], v[130:133]
	v_mfma_i32_16x16x64_i8 v[118:121], v[150:153], v[174:177], v[118:121]
	v_mfma_i32_16x16x64_i8 v[114:117], v[158:161], v[174:177], v[114:117]
	v_mfma_i32_16x16x64_i8 v[86:89], v[150:153], v[206:209], v[86:89]
	v_mfma_i32_16x16x64_i8 v[82:85], v[158:161], v[206:209], v[82:85]
	v_mfma_i32_16x16x64_i8 v[70:73], v[150:153], v[214:217], v[70:73]
	v_mfma_i32_16x16x64_i8 v[66:69], v[158:161], v[214:217], v[66:69]
	s_setprio 0
	s_barrier
	s_add_u32 s98, s26, 0xfffe0080
	s_addc_u32 s99, s27, -1
	s_add_i32 s26, s67, s29
	s_mov_b32 m0, s26
	ds_read_b128 v[162:165], v205 offset:49152
	ds_read_b128 v[166:169], v205 offset:50176
	ds_read_b128 v[170:173], v205 offset:51200
	ds_read_b128 v[174:177], v205 offset:52224
	ds_read_b128 v[178:181], v205 offset:53248
	ds_read_b128 v[206:209], v205 offset:54272
	ds_read_b128 v[210:213], v205 offset:55296
	ds_read_b128 v[214:217], v205 offset:56320
	s_add_u32 s100, s24, 0x80
	s_addc_u32 s101, s25, 0
	global_load_lds_dwordx4 v184, s[100:101]
	s_add_i32 m0, s26, 0x2000
	s_add_u32 s24, s24, 0x20080
	s_addc_u32 s25, s25, 0
	s_add_i32 s26, s68, s29
	global_load_lds_dwordx4 v186, s[100:101]
	s_mov_b32 m0, s26
	s_nop 0
	global_load_lds_dwordx4 v184, s[24:25]
	s_add_i32 m0, s26, 0x2000
	s_nop 0
	global_load_lds_dwordx4 v186, s[24:25]
	s_mov_b32 m0, s38
	s_nop 0
	global_load_lds_dwordx4 v184, s[98:99]
	s_mov_b32 m0, s39
	s_nop 0
	global_load_lds_dwordx4 v186, s[98:99]
	s_waitcnt vmcnt(8)
	s_waitcnt lgkmcnt(0)
	s_barrier
	s_setprio 1
	s_waitcnt lgkmcnt(0)
	v_mfma_i32_16x16x64_i8 v[62:65], v[90:93], v[162:165], v[62:65]
	v_mfma_i32_16x16x64_i8 v[58:61], v[102:105], v[162:165], v[58:61]
	v_mfma_i32_16x16x64_i8 v[46:49], v[90:93], v[170:173], v[46:49]
	v_mfma_i32_16x16x64_i8 v[42:45], v[102:105], v[170:173], v[42:45]
	v_mfma_i32_16x16x64_i8 v[30:33], v[90:93], v[178:181], v[30:33]
	v_mfma_i32_16x16x64_i8 v[26:29], v[102:105], v[178:181], v[26:29]
	v_mfma_i32_16x16x64_i8 v[14:17], v[90:93], v[210:213], v[14:17]
	v_mfma_i32_16x16x64_i8 v[10:13], v[102:105], v[210:213], v[10:13]
	v_mfma_i32_16x16x64_i8 v[62:65], v[98:101], v[166:169], v[62:65]
	v_mfma_i32_16x16x64_i8 v[58:61], v[142:145], v[166:169], v[58:61]
	v_mfma_i32_16x16x64_i8 v[46:49], v[98:101], v[174:177], v[46:49]
	v_mfma_i32_16x16x64_i8 v[42:45], v[142:145], v[174:177], v[42:45]
	v_mfma_i32_16x16x64_i8 v[30:33], v[98:101], v[206:209], v[30:33]
	v_mfma_i32_16x16x64_i8 v[26:29], v[142:145], v[206:209], v[26:29]
	v_mfma_i32_16x16x64_i8 v[14:17], v[98:101], v[214:217], v[14:17]
	v_mfma_i32_16x16x64_i8 v[10:13], v[142:145], v[214:217], v[10:13]
	s_setprio 0
	s_setprio 1
	v_mfma_i32_16x16x64_i8 v[54:57], v[146:149], v[162:165], v[54:57]
	v_mfma_i32_16x16x64_i8 v[50:53], v[154:157], v[162:165], v[50:53]
	v_mfma_i32_16x16x64_i8 v[38:41], v[146:149], v[170:173], v[38:41]
	v_mfma_i32_16x16x64_i8 v[34:37], v[154:157], v[170:173], v[34:37]
	v_mfma_i32_16x16x64_i8 v[22:25], v[146:149], v[178:181], v[22:25]
	v_mfma_i32_16x16x64_i8 v[18:21], v[154:157], v[178:181], v[18:21]
	v_mfma_i32_16x16x64_i8 v[6:9], v[146:149], v[210:213], v[6:9]
	v_mfma_i32_16x16x64_i8 v[2:5], v[154:157], v[210:213], v[2:5]
	v_mfma_i32_16x16x64_i8 v[54:57], v[150:153], v[166:169], v[54:57]
	v_mfma_i32_16x16x64_i8 v[50:53], v[158:161], v[166:169], v[50:53]
	v_mfma_i32_16x16x64_i8 v[38:41], v[150:153], v[174:177], v[38:41]
	v_mfma_i32_16x16x64_i8 v[34:37], v[158:161], v[174:177], v[34:37]
	v_mfma_i32_16x16x64_i8 v[22:25], v[150:153], v[206:209], v[22:25]
	v_mfma_i32_16x16x64_i8 v[18:21], v[158:161], v[206:209], v[18:21]
	v_mfma_i32_16x16x64_i8 v[6:9], v[150:153], v[214:217], v[6:9]
	v_mfma_i32_16x16x64_i8 v[2:5], v[158:161], v[214:217], v[2:5]
	s_setprio 0
	s_barrier
	s_add_i32 s66, s66, 2
	s_add_u32 s22, s22, 0x100
	s_addc_u32 s23, s23, 0
	s_add_u32 s56, s56, 0x100
	s_addc_u32 s57, s57, 0
	s_cmp_gt_u32 s66, 5

.LBB0_708:
	s_ashr_i32 s27, s26, 31
	s_lshl_b64 s[28:29], s[26:27], 20
	s_add_u32 s28, s50, s28
	s_addc_u32 s29, s51, s29
	s_and_b64 s[30:31], s[2:3], exec
	s_cselect_b32 s27, s29, s37
	s_cselect_b32 s74, s28, s36
	s_ashr_i32 s25, s24, 31
	s_lshl_b64 s[30:31], s[24:25], 20
	s_add_u32 s30, s84, s30
	s_addc_u32 s31, s86, s31
	s_and_b64 s[40:41], s[2:3], exec
	s_cselect_b32 s25, s31, s39
	s_cselect_b32 s75, s30, s38
	s_add_u32 s36, s36, 0x80080
	s_addc_u32 s37, s37, 0
	s_add_u32 s76, s38, 0x100
	s_addc_u32 s77, s39, 0
	s_mov_b32 s78, -2
	ds_read_b128 v[130:133], v178
	ds_read_b128 v[134:137], v178 offset:1024
	ds_read_b128 v[138:141], v178 offset:2048
	ds_read_b128 v[142:145], v178 offset:3072
	ds_read_b128 v[146:149], v179
	ds_read_b128 v[150:153], v179 offset:1024
	ds_read_b128 v[154:157], v179 offset:2048
	ds_read_b128 v[158:161], v179 offset:3072
	s_add_u32 s38, s36, 0xfff80080
	s_addc_u32 s39, s37, -1
	s_cmp_eq_u32 s78, 28
	s_cselect_b32 s41, s27, s39
	s_cselect_b32 s40, s74, s38
	s_cselect_b32 s39, s25, s77
	s_cselect_b32 s38, s75, s76
	s_add_i32 m0, s35, 0xc000
	ds_read_b128 v[184:187], v180
	ds_read_b128 v[188:191], v180 offset:1024
	ds_read_b128 v[192:195], v180 offset:2048
	ds_read_b128 v[196:199], v180 offset:3072
	ds_read_b128 v[200:203], v180 offset:4096
	ds_read_b128 v[204:207], v180 offset:5120
	ds_read_b128 v[208:211], v180 offset:6144
	ds_read_b128 v[212:215], v180 offset:7168
	global_load_lds_dwordx4 v168, s[36:37]
	s_add_i32 m0, s35, 0xe000
	s_nop 0
	global_load_lds_dwordx4 v170, s[36:37]
	s_cmp_lg_u32 s32, 0
	s_cbranch_scc1 .Lpw3a
	s_waitcnt vmcnt(8)
.Lpw3a:
	s_waitcnt lgkmcnt(0)
	s_barrier
	s_setprio 1
	s_waitcnt lgkmcnt(0)
	v_mfma_i32_16x16x64_i8 v[126:129], v[130:133], v[184:187], 0
	v_mfma_i32_16x16x64_i8 v[122:125], v[138:141], v[184:187], 0
	v_mfma_i32_16x16x64_i8 v[110:113], v[130:133], v[192:195], 0
	v_mfma_i32_16x16x64_i8 v[106:109], v[138:141], v[192:195], 0
	v_mfma_i32_16x16x64_i8 v[94:97], v[130:133], v[200:203], 0
	v_mfma_i32_16x16x64_i8 v[90:93], v[138:141], v[200:203], 0
	v_mfma_i32_16x16x64_i8 v[78:81], v[130:133], v[208:211], 0
	v_mfma_i32_16x16x64_i8 v[74:77], v[138:141], v[208:211], 0
	v_mfma_i32_16x16x64_i8 v[126:129], v[134:137], v[188:191], v[126:129]
	v_mfma_i32_16x16x64_i8 v[122:125], v[142:145], v[188:191], v[122:125]
	v_mfma_i32_16x16x64_i8 v[110:113], v[134:137], v[196:199], v[110:113]
	v_mfma_i32_16x16x64_i8 v[106:109], v[142:145], v[196:199], v[106:109]
	v_mfma_i32_16x16x64_i8 v[94:97], v[134:137], v[204:207], v[94:97]
	v_mfma_i32_16x16x64_i8 v[90:93], v[142:145], v[204:207], v[90:93]
	v_mfma_i32_16x16x64_i8 v[78:81], v[134:137], v[212:215], v[78:81]
	v_mfma_i32_16x16x64_i8 v[74:77], v[142:145], v[212:215], v[74:77]
	s_setprio 0
	s_setprio 1
	v_mfma_i32_16x16x64_i8 v[118:121], v[146:149], v[184:187], 0
	v_mfma_i32_16x16x64_i8 v[114:117], v[154:157], v[184:187], 0
	v_mfma_i32_16x16x64_i8 v[102:105], v[146:149], v[192:195], 0
	v_mfma_i32_16x16x64_i8 v[98:101], v[154:157], v[192:195], 0
	v_mfma_i32_16x16x64_i8 v[86:89], v[146:149], v[200:203], 0
	v_mfma_i32_16x16x64_i8 v[82:85], v[154:157], v[200:203], 0
	v_mfma_i32_16x16x64_i8 v[70:73], v[146:149], v[208:211], 0
	v_mfma_i32_16x16x64_i8 v[66:69], v[154:157], v[208:211], 0
	v_mfma_i32_16x16x64_i8 v[118:121], v[150:153], v[188:191], v[118:121]
	v_mfma_i32_16x16x64_i8 v[114:117], v[158:161], v[188:191], v[114:117]
	v_mfma_i32_16x16x64_i8 v[102:105], v[150:153], v[196:199], v[102:105]
	v_mfma_i32_16x16x64_i8 v[98:101], v[158:161], v[196:199], v[98:101]
	v_mfma_i32_16x16x64_i8 v[86:89], v[150:153], v[204:207], v[86:89]
	v_mfma_i32_16x16x64_i8 v[82:85], v[158:161], v[204:207], v[82:85]
	v_mfma_i32_16x16x64_i8 v[70:73], v[150:153], v[212:215], v[70:73]
	v_mfma_i32_16x16x64_i8 v[66:69], v[158:161], v[212:215], v[66:69]
	s_setprio 0
	s_barrier
	s_add_i32 s79, s0, s42
	s_mov_b32 m0, s79
	ds_read_b128 v[184:187], v180 offset:16384
	ds_read_b128 v[188:191], v180 offset:17408
	ds_read_b128 v[192:195], v180 offset:18432
	ds_read_b128 v[196:199], v180 offset:19456
	ds_read_b128 v[200:203], v180 offset:20480
	ds_read_b128 v[204:207], v180 offset:21504
	ds_read_b128 v[208:211], v180 offset:22528
	ds_read_b128 v[212:215], v180 offset:23552
	global_load_lds_dwordx4 v162, s[38:39]
	s_add_i32 m0, s79, 0x2000
	s_add_u32 s82, s38, 0x80000
	s_addc_u32 s83, s39, 0
	s_add_i32 s79, s68, s42
	global_load_lds_dwordx4 v164, s[38:39]
	s_mov_b32 m0, s79
	s_nop 0
	global_load_lds_dwordx4 v162, s[82:83]
	s_add_i32 m0, s79, 0x2000
	s_nop 0
	global_load_lds_dwordx4 v164, s[82:83]
	s_mov_b32 m0, s35
	s_nop 0
	global_load_lds_dwordx4 v162, s[40:41]
	s_mov_b32 m0, s46
	s_nop 0
	global_load_lds_dwordx4 v164, s[40:41]
	s_cmp_lg_u32 s32, 0
	s_cbranch_scc1 .Lpw3b
	s_waitcnt vmcnt(8)
.Lpw3b:
	s_mov_b32 s32, 1
	s_waitcnt lgkmcnt(0)
	s_barrier
	s_setprio 1
	s_waitcnt lgkmcnt(0)
	v_mfma_i32_16x16x64_i8 v[62:65], v[130:133], v[184:187], 0
	v_mfma_i32_16x16x64_i8 v[58:61], v[138:141], v[184:187], 0
	v_mfma_i32_16x16x64_i8 v[50:53], v[130:133], v[192:195], 0
	v_mfma_i32_16x16x64_i8 v[42:45], v[138:141], v[192:195], 0
	v_mfma_i32_16x16x64_i8 v[34:37], v[130:133], v[200:203], 0
	v_mfma_i32_16x16x64_i8 v[26:29], v[138:141], v[200:203], 0
	v_mfma_i32_16x16x64_i8 v[18:21], v[130:133], v[208:211], 0
	v_mfma_i32_16x16x64_i8 v[10:13], v[138:141], v[208:211], 0
	v_mfma_i32_16x16x64_i8 v[62:65], v[134:137], v[188:191], v[62:65]
	v_mfma_i32_16x16x64_i8 v[58:61], v[142:145], v[188:191], v[58:61]
	v_mfma_i32_16x16x64_i8 v[50:53], v[134:137], v[196:199], v[50:53]
	v_mfma_i32_16x16x64_i8 v[42:45], v[142:145], v[196:199], v[42:45]
	v_mfma_i32_16x16x64_i8 v[34:37], v[134:137], v[204:207], v[34:37]
	v_mfma_i32_16x16x64_i8 v[26:29], v[142:145], v[204:207], v[26:29]
	v_mfma_i32_16x16x64_i8 v[18:21], v[134:137], v[212:215], v[18:21]
	v_mfma_i32_16x16x64_i8 v[10:13], v[142:145], v[212:215], v[10:13]
	s_setprio 0
	s_setprio 1
	v_mfma_i32_16x16x64_i8 v[54:57], v[146:149], v[184:187], 0
	v_mfma_i32_16x16x64_i8 v[46:49], v[154:157], v[184:187], 0
	v_mfma_i32_16x16x64_i8 v[38:41], v[146:149], v[192:195], 0
	v_mfma_i32_16x16x64_i8 v[30:33], v[154:157], v[192:195], 0
	v_mfma_i32_16x16x64_i8 v[22:25], v[146:149], v[200:203], 0
	v_mfma_i32_16x16x64_i8 v[14:17], v[154:157], v[200:203], 0
	v_mfma_i32_16x16x64_i8 v[6:9], v[146:149], v[208:211], 0
	v_mfma_i32_16x16x64_i8 v[2:5], v[154:157], v[208:211], 0
	v_mfma_i32_16x16x64_i8 v[54:57], v[150:153], v[188:191], v[54:57]
	v_mfma_i32_16x16x64_i8 v[46:49], v[158:161], v[188:191], v[46:49]
	v_mfma_i32_16x16x64_i8 v[38:41], v[150:153], v[196:199], v[38:41]
	v_mfma_i32_16x16x64_i8 v[30:33], v[158:161], v[196:199], v[30:33]
	v_mfma_i32_16x16x64_i8 v[22:25], v[150:153], v[204:207], v[22:25]
	v_mfma_i32_16x16x64_i8 v[14:17], v[158:161], v[204:207], v[14:17]
	v_mfma_i32_16x16x64_i8 v[6:9], v[150:153], v[212:215], v[6:9]
	v_mfma_i32_16x16x64_i8 v[2:5], v[158:161], v[212:215], v[2:5]
	s_setprio 0
	s_barrier
	s_add_i32 s79, 0, 0x18000
	s_add_i32 s80, 0, 0x1c000
	v_add_u32_e32 v142, s79, v176
	v_add_u32_e32 v158, s80, v176
	ds_read_b128 v[130:133], v142
	ds_read_b128 v[134:137], v142 offset:1024
	ds_read_b128 v[138:141], v142 offset:2048
	ds_read_b128 v[142:145], v142 offset:3072
	ds_read_b128 v[146:149], v158
	ds_read_b128 v[150:153], v158 offset:1024
	ds_read_b128 v[154:157], v158 offset:2048
	ds_read_b128 v[158:161], v158 offset:3072
	s_add_u32 s40, s40, 0x80000
	s_addc_u32 s41, s41, 0
	s_mov_b32 m0, s47
	ds_read_b128 v[184:187], v180 offset:32768
	ds_read_b128 v[188:191], v180 offset:33792
	ds_read_b128 v[192:195], v180 offset:34816
	ds_read_b128 v[196:199], v180 offset:35840
	ds_read_b128 v[200:203], v180 offset:36864
	ds_read_b128 v[204:207], v180 offset:37888
	ds_read_b128 v[208:211], v180 offset:38912
	ds_read_b128 v[212:215], v180 offset:39936
	global_load_lds_dwordx4 v162, s[40:41]
	s_mov_b32 m0, s54
	s_nop 0
	global_load_lds_dwordx4 v164, s[40:41]
	s_waitcnt vmcnt(8)
	s_waitcnt lgkmcnt(0)
	s_barrier
	s_setprio 1
	s_waitcnt lgkmcnt(0)
	v_mfma_i32_16x16x64_i8 v[126:129], v[130:133], v[184:187], v[126:129]
	v_mfma_i32_16x16x64_i8 v[122:125], v[138:141], v[184:187], v[122:125]
	v_mfma_i32_16x16x64_i8 v[110:113], v[130:133], v[192:195], v[110:113]
	v_mfma_i32_16x16x64_i8 v[106:109], v[138:141], v[192:195], v[106:109]
	v_mfma_i32_16x16x64_i8 v[94:97], v[130:133], v[200:203], v[94:97]
	v_mfma_i32_16x16x64_i8 v[90:93], v[138:141], v[200:203], v[90:93]
	v_mfma_i32_16x16x64_i8 v[78:81], v[130:133], v[208:211], v[78:81]
	v_mfma_i32_16x16x64_i8 v[74:77], v[138:141], v[208:211], v[74:77]
	v_mfma_i32_16x16x64_i8 v[126:129], v[134:137], v[188:191], v[126:129]
	v_mfma_i32_16x16x64_i8 v[122:125], v[142:145], v[188:191], v[122:125]
	v_mfma_i32_16x16x64_i8 v[110:113], v[134:137], v[196:199], v[110:113]
	v_mfma_i32_16x16x64_i8 v[106:109], v[142:145], v[196:199], v[106:109]
	v_mfma_i32_16x16x64_i8 v[94:97], v[134:137], v[204:207], v[94:97]
	v_mfma_i32_16x16x64_i8 v[90:93], v[142:145], v[204:207], v[90:93]
	v_mfma_i32_16x16x64_i8 v[78:81], v[134:137], v[212:215], v[78:81]
	v_mfma_i32_16x16x64_i8 v[74:77], v[142:145], v[212:215], v[74:77]
	s_setprio 0
	s_setprio 1
	v_mfma_i32_16x16x64_i8 v[118:121], v[146:149], v[184:187], v[118:121]
	v_mfma_i32_16x16x64_i8 v[114:117], v[154:157], v[184:187], v[114:117]
	v_mfma_i32_16x16x64_i8 v[102:105], v[146:149], v[192:195], v[102:105]
	v_mfma_i32_16x16x64_i8 v[98:101], v[154:157], v[192:195], v[98:101]
	v_mfma_i32_16x16x64_i8 v[86:89], v[146:149], v[200:203], v[86:89]
	v_mfma_i32_16x16x64_i8 v[82:85], v[154:157], v[200:203], v[82:85]
	v_mfma_i32_16x16x64_i8 v[70:73], v[146:149], v[208:211], v[70:73]
	v_mfma_i32_16x16x64_i8 v[66:69], v[154:157], v[208:211], v[66:69]
	v_mfma_i32_16x16x64_i8 v[118:121], v[150:153], v[188:191], v[118:121]
	v_mfma_i32_16x16x64_i8 v[114:117], v[158:161], v[188:191], v[114:117]
	v_mfma_i32_16x16x64_i8 v[102:105], v[150:153], v[196:199], v[102:105]
	v_mfma_i32_16x16x64_i8 v[98:101], v[158:161], v[196:199], v[98:101]
	v_mfma_i32_16x16x64_i8 v[86:89], v[150:153], v[204:207], v[86:89]
	v_mfma_i32_16x16x64_i8 v[82:85], v[158:161], v[204:207], v[82:85]
	v_mfma_i32_16x16x64_i8 v[70:73], v[150:153], v[212:215], v[70:73]
	v_mfma_i32_16x16x64_i8 v[66:69], v[158:161], v[212:215], v[66:69]
	s_setprio 0
	s_barrier
	s_add_u32 s98, s40, 0xfff80080
	s_addc_u32 s99, s41, -1
	s_add_i32 s40, s79, s42
	s_mov_b32 m0, s40
	ds_read_b128 v[184:187], v180 offset:49152
	ds_read_b128 v[188:191], v180 offset:50176
	ds_read_b128 v[192:195], v180 offset:51200
	ds_read_b128 v[196:199], v180 offset:52224
	ds_read_b128 v[200:203], v180 offset:53248
	ds_read_b128 v[204:207], v180 offset:54272
	ds_read_b128 v[208:211], v180 offset:55296
	ds_read_b128 v[212:215], v180 offset:56320
	s_add_u32 s100, s38, 0x80
	s_addc_u32 s101, s39, 0
	global_load_lds_dwordx4 v162, s[100:101]
	s_add_i32 m0, s40, 0x2000
	s_add_u32 s38, s38, 0x80080
	s_addc_u32 s39, s39, 0
	s_add_i32 s40, s80, s42
	global_load_lds_dwordx4 v164, s[100:101]
	s_mov_b32 m0, s40
	s_nop 0
	global_load_lds_dwordx4 v162, s[38:39]
	s_add_i32 m0, s40, 0x2000
	s_nop 0
	global_load_lds_dwordx4 v164, s[38:39]
	s_mov_b32 m0, s66
	s_nop 0
	global_load_lds_dwordx4 v162, s[98:99]
	s_mov_b32 m0, s67
	s_nop 0
	global_load_lds_dwordx4 v164, s[98:99]
	s_waitcnt vmcnt(8)
	s_waitcnt lgkmcnt(0)
	s_barrier
	s_setprio 1
	s_waitcnt lgkmcnt(0)
	v_mfma_i32_16x16x64_i8 v[62:65], v[130:133], v[184:187], v[62:65]
	v_mfma_i32_16x16x64_i8 v[58:61], v[138:141], v[184:187], v[58:61]
	v_mfma_i32_16x16x64_i8 v[50:53], v[130:133], v[192:195], v[50:53]
	v_mfma_i32_16x16x64_i8 v[42:45], v[138:141], v[192:195], v[42:45]
	v_mfma_i32_16x16x64_i8 v[34:37], v[130:133], v[200:203], v[34:37]
	v_mfma_i32_16x16x64_i8 v[26:29], v[138:141], v[200:203], v[26:29]
	v_mfma_i32_16x16x64_i8 v[18:21], v[130:133], v[208:211], v[18:21]
	v_mfma_i32_16x16x64_i8 v[10:13], v[138:141], v[208:211], v[10:13]
	v_mfma_i32_16x16x64_i8 v[62:65], v[134:137], v[188:191], v[62:65]
	v_mfma_i32_16x16x64_i8 v[58:61], v[142:145], v[188:191], v[58:61]
	v_mfma_i32_16x16x64_i8 v[50:53], v[134:137], v[196:199], v[50:53]
	v_mfma_i32_16x16x64_i8 v[42:45], v[142:145], v[196:199], v[42:45]
	v_mfma_i32_16x16x64_i8 v[34:37], v[134:137], v[204:207], v[34:37]
	v_mfma_i32_16x16x64_i8 v[26:29], v[142:145], v[204:207], v[26:29]
	v_mfma_i32_16x16x64_i8 v[18:21], v[134:137], v[212:215], v[18:21]
	v_mfma_i32_16x16x64_i8 v[10:13], v[142:145], v[212:215], v[10:13]
	s_setprio 0
	s_setprio 1
	v_mfma_i32_16x16x64_i8 v[54:57], v[146:149], v[184:187], v[54:57]
	v_mfma_i32_16x16x64_i8 v[46:49], v[154:157], v[184:187], v[46:49]
	v_mfma_i32_16x16x64_i8 v[38:41], v[146:149], v[192:195], v[38:41]
	v_mfma_i32_16x16x64_i8 v[30:33], v[154:157], v[192:195], v[30:33]
	v_mfma_i32_16x16x64_i8 v[22:25], v[146:149], v[200:203], v[22:25]
	v_mfma_i32_16x16x64_i8 v[14:17], v[154:157], v[200:203], v[14:17]
	v_mfma_i32_16x16x64_i8 v[6:9], v[146:149], v[208:211], v[6:9]
	v_mfma_i32_16x16x64_i8 v[2:5], v[154:157], v[208:211], v[2:5]
	v_mfma_i32_16x16x64_i8 v[54:57], v[150:153], v[188:191], v[54:57]
	v_mfma_i32_16x16x64_i8 v[46:49], v[158:161], v[188:191], v[46:49]
	v_mfma_i32_16x16x64_i8 v[38:41], v[150:153], v[196:199], v[38:41]
	v_mfma_i32_16x16x64_i8 v[30:33], v[158:161], v[196:199], v[30:33]
	v_mfma_i32_16x16x64_i8 v[22:25], v[150:153], v[204:207], v[22:25]
	v_mfma_i32_16x16x64_i8 v[14:17], v[158:161], v[204:207], v[14:17]
	v_mfma_i32_16x16x64_i8 v[6:9], v[150:153], v[212:215], v[6:9]
	v_mfma_i32_16x16x64_i8 v[2:5], v[158:161], v[212:215], v[2:5]
	s_setprio 0
	s_barrier
	s_add_i32 s78, s78, 2
	s_add_u32 s36, s36, 0x100
	s_addc_u32 s37, s37, 0
	s_add_u32 s76, s76, 0x100
	s_addc_u32 s77, s77, 0
	s_cmp_gt_u32 s78, 29

.LBB0_847:
	s_ashr_i32 s23, s22, 31
	s_lshl_b64 s[24:25], s[22:23], 20
	s_add_u32 s24, s20, s24
	s_addc_u32 s25, s21, s25
	s_and_b64 s[26:27], s[2:3], exec
	s_cselect_b32 s23, s25, s31
	s_cselect_b32 s66, s24, s30
	s_ashr_i32 s19, s18, 31
	s_lshl_b64 s[26:27], s[18:19], 20
	v_readlane_b32 s68, v254, 24
	s_add_u32 s26, s68, s26
	s_addc_u32 s27, s74, s27
	s_and_b64 s[36:37], s[2:3], exec
	s_cselect_b32 s19, s27, s35
	s_cselect_b32 s67, s26, s34
	s_add_u32 s30, s30, 0x80080
	s_addc_u32 s31, s31, 0
	v_readlane_b32 s69, v254, 25
	v_readlane_b32 s70, v254, 26
	s_add_u32 s68, s34, 0x100
	s_addc_u32 s69, s35, 0
	s_mov_b32 s70, -2
	v_readlane_b32 s71, v254, 27
	ds_read_b128 v[106:109], v173
	ds_read_b128 v[110:113], v173 offset:1024
	ds_read_b128 v[122:125], v173 offset:2048
	ds_read_b128 v[126:129], v173 offset:3072
	ds_read_b128 v[176:179], v174
	ds_read_b128 v[184:187], v174 offset:1024
	ds_read_b128 v[188:191], v174 offset:2048
	ds_read_b128 v[192:195], v174 offset:3072
	s_add_u32 s34, s30, 0xfff80080
	s_addc_u32 s35, s31, -1
	s_cmp_eq_u32 s70, 28
	s_cselect_b32 s37, s23, s35
	s_cselect_b32 s36, s66, s34
	s_cselect_b32 s35, s19, s69
	s_cselect_b32 s34, s67, s68
	s_add_i32 m0, s29, 0xc000
	ds_read_b128 v[196:199], v175
	ds_read_b128 v[200:203], v175 offset:1024
	ds_read_b128 v[204:207], v175 offset:2048
	ds_read_b128 v[208:211], v175 offset:3072
	ds_read_b128 v[212:215], v175 offset:4096
	ds_read_b128 v[216:219], v175 offset:5120
	ds_read_b128 v[220:223], v175 offset:6144
	ds_read_b128 v[224:227], v175 offset:7168
	global_load_lds_dwordx4 v152, s[30:31]
	s_add_i32 m0, s29, 0xe000
	s_nop 0
	global_load_lds_dwordx4 v154, s[30:31]
	s_cmp_lg_u32 s32, 0
	s_cbranch_scc1 .Lpw4a
	s_waitcnt vmcnt(8)
.Lpw4a:
	s_waitcnt lgkmcnt(0)
	s_barrier
	s_setprio 1
	s_waitcnt lgkmcnt(0)
	v_mfma_i32_16x16x64_i8 v[142:145], v[106:109], v[196:199], 0
	v_mfma_i32_16x16x64_i8 v[138:141], v[122:125], v[196:199], 0
	v_mfma_i32_16x16x64_i8 v[118:121], v[106:109], v[204:207], 0
	v_mfma_i32_16x16x64_i8 v[114:117], v[122:125], v[204:207], 0
	v_mfma_i32_16x16x64_i8 v[94:97], v[106:109], v[212:215], 0
	v_mfma_i32_16x16x64_i8 v[90:93], v[122:125], v[212:215], 0
	v_mfma_i32_16x16x64_i8 v[78:81], v[106:109], v[220:223], 0
	v_mfma_i32_16x16x64_i8 v[74:77], v[122:125], v[220:223], 0
	v_mfma_i32_16x16x64_i8 v[142:145], v[110:113], v[200:203], v[142:145]
	v_mfma_i32_16x16x64_i8 v[138:141], v[126:129], v[200:203], v[138:141]
	v_mfma_i32_16x16x64_i8 v[118:121], v[110:113], v[208:211], v[118:121]
	v_mfma_i32_16x16x64_i8 v[114:117], v[126:129], v[208:211], v[114:117]
	v_mfma_i32_16x16x64_i8 v[94:97], v[110:113], v[216:219], v[94:97]
	v_mfma_i32_16x16x64_i8 v[90:93], v[126:129], v[216:219], v[90:93]
	v_mfma_i32_16x16x64_i8 v[78:81], v[110:113], v[224:227], v[78:81]
	v_mfma_i32_16x16x64_i8 v[74:77], v[126:129], v[224:227], v[74:77]
	s_setprio 0
	s_setprio 1
	v_mfma_i32_16x16x64_i8 v[134:137], v[176:179], v[196:199], 0
	v_mfma_i32_16x16x64_i8 v[130:133], v[188:191], v[196:199], 0
	v_mfma_i32_16x16x64_i8 v[102:105], v[176:179], v[204:207], 0
	v_mfma_i32_16x16x64_i8 v[98:101], v[188:191], v[204:207], 0
	v_mfma_i32_16x16x64_i8 v[86:89], v[176:179], v[212:215], 0
	v_mfma_i32_16x16x64_i8 v[82:85], v[188:191], v[212:215], 0
	v_mfma_i32_16x16x64_i8 v[70:73], v[176:179], v[220:223], 0
	v_mfma_i32_16x16x64_i8 v[66:69], v[188:191], v[220:223], 0
	v_mfma_i32_16x16x64_i8 v[134:137], v[184:187], v[200:203], v[134:137]
	v_mfma_i32_16x16x64_i8 v[130:133], v[192:195], v[200:203], v[130:133]
	v_mfma_i32_16x16x64_i8 v[102:105], v[184:187], v[208:211], v[102:105]
	v_mfma_i32_16x16x64_i8 v[98:101], v[192:195], v[208:211], v[98:101]
	v_mfma_i32_16x16x64_i8 v[86:89], v[184:187], v[216:219], v[86:89]
	v_mfma_i32_16x16x64_i8 v[82:85], v[192:195], v[216:219], v[82:85]
	v_mfma_i32_16x16x64_i8 v[70:73], v[184:187], v[224:227], v[70:73]
	v_mfma_i32_16x16x64_i8 v[66:69], v[192:195], v[224:227], v[66:69]
	s_setprio 0
	s_barrier
	s_add_i32 s71, s51, s39
	s_mov_b32 m0, s71
	ds_read_b128 v[196:199], v175 offset:16384
	ds_read_b128 v[200:203], v175 offset:17408
	ds_read_b128 v[204:207], v175 offset:18432
	ds_read_b128 v[208:211], v175 offset:19456
	ds_read_b128 v[212:215], v175 offset:20480
	ds_read_b128 v[216:219], v175 offset:21504
	ds_read_b128 v[220:223], v175 offset:22528
	ds_read_b128 v[224:227], v175 offset:23552
	global_load_lds_dwordx4 v146, s[34:35]
	s_add_i32 m0, s71, 0x2000
	s_add_u32 s72, s34, 0x80000
	s_addc_u32 s73, s35, 0
	s_add_i32 s71, s52, s39
	global_load_lds_dwordx4 v148, s[34:35]
	s_mov_b32 m0, s71
	s_nop 0
	global_load_lds_dwordx4 v146, s[72:73]
	s_add_i32 m0, s71, 0x2000
	s_nop 0
	global_load_lds_dwordx4 v148, s[72:73]
	s_mov_b32 m0, s29
	s_nop 0
	global_load_lds_dwordx4 v146, s[36:37]
	s_mov_b32 m0, s40
	s_nop 0
	global_load_lds_dwordx4 v148, s[36:37]
	s_cmp_lg_u32 s32, 0
	s_cbranch_scc1 .Lpw4b
	s_waitcnt vmcnt(8)
.Lpw4b:
	s_mov_b32 s32, 1
	s_waitcnt lgkmcnt(0)
	s_barrier
	s_setprio 1
	s_waitcnt lgkmcnt(0)
	v_mfma_i32_16x16x64_i8 v[62:65], v[106:109], v[196:199], 0
	v_mfma_i32_16x16x64_i8 v[58:61], v[122:125], v[196:199], 0
	v_mfma_i32_16x16x64_i8 v[46:49], v[106:109], v[204:207], 0
	v_mfma_i32_16x16x64_i8 v[42:45], v[122:125], v[204:207], 0
	v_mfma_i32_16x16x64_i8 v[30:33], v[106:109], v[212:215], 0
	v_mfma_i32_16x16x64_i8 v[26:29], v[122:125], v[212:215], 0
	v_mfma_i32_16x16x64_i8 v[14:17], v[106:109], v[220:223], 0
	v_mfma_i32_16x16x64_i8 v[10:13], v[122:125], v[220:223], 0
	v_mfma_i32_16x16x64_i8 v[62:65], v[110:113], v[200:203], v[62:65]
	v_mfma_i32_16x16x64_i8 v[58:61], v[126:129], v[200:203], v[58:61]
	v_mfma_i32_16x16x64_i8 v[46:49], v[110:113], v[208:211], v[46:49]
	v_mfma_i32_16x16x64_i8 v[42:45], v[126:129], v[208:211], v[42:45]
	v_mfma_i32_16x16x64_i8 v[30:33], v[110:113], v[216:219], v[30:33]
	v_mfma_i32_16x16x64_i8 v[26:29], v[126:129], v[216:219], v[26:29]
	v_mfma_i32_16x16x64_i8 v[14:17], v[110:113], v[224:227], v[14:17]
	v_mfma_i32_16x16x64_i8 v[10:13], v[126:129], v[224:227], v[10:13]
	s_setprio 0
	s_setprio 1
	v_mfma_i32_16x16x64_i8 v[54:57], v[176:179], v[196:199], 0
	v_mfma_i32_16x16x64_i8 v[50:53], v[188:191], v[196:199], 0
	v_mfma_i32_16x16x64_i8 v[38:41], v[176:179], v[204:207], 0
	v_mfma_i32_16x16x64_i8 v[34:37], v[188:191], v[204:207], 0
	v_mfma_i32_16x16x64_i8 v[22:25], v[176:179], v[212:215], 0
	v_mfma_i32_16x16x64_i8 v[18:21], v[188:191], v[212:215], 0
	v_mfma_i32_16x16x64_i8 v[6:9], v[176:179], v[220:223], 0
	v_mfma_i32_16x16x64_i8 v[2:5], v[188:191], v[220:223], 0
	v_mfma_i32_16x16x64_i8 v[54:57], v[184:187], v[200:203], v[54:57]
	v_mfma_i32_16x16x64_i8 v[50:53], v[192:195], v[200:203], v[50:53]
	v_mfma_i32_16x16x64_i8 v[38:41], v[184:187], v[208:211], v[38:41]
	v_mfma_i32_16x16x64_i8 v[34:37], v[192:195], v[208:211], v[34:37]
	v_mfma_i32_16x16x64_i8 v[22:25], v[184:187], v[216:219], v[22:25]
	v_mfma_i32_16x16x64_i8 v[18:21], v[192:195], v[216:219], v[18:21]
	v_mfma_i32_16x16x64_i8 v[6:9], v[184:187], v[224:227], v[6:9]
	v_mfma_i32_16x16x64_i8 v[2:5], v[192:195], v[224:227], v[2:5]
	s_setprio 0
	s_barrier
	s_add_i32 s71, 0, 0x18000
	s_add_i32 s72, 0, 0x1c000
	v_add_u32_e32 v126, s71, v171
	v_add_u32_e32 v160, s72, v171
	ds_read_b128 v[106:109], v126
	ds_read_b128 v[110:113], v126 offset:1024
	ds_read_b128 v[122:125], v126 offset:2048
	ds_read_b128 v[126:129], v126 offset:3072
	ds_read_b128 v[176:179], v160
	ds_read_b128 v[184:187], v160 offset:1024
	ds_read_b128 v[188:191], v160 offset:2048
	ds_read_b128 v[192:195], v160 offset:3072
	s_add_u32 s36, s36, 0x80000
	s_addc_u32 s37, s37, 0
	s_mov_b32 m0, s41
	ds_read_b128 v[196:199], v175 offset:32768
	ds_read_b128 v[200:203], v175 offset:33792
	ds_read_b128 v[204:207], v175 offset:34816
	ds_read_b128 v[208:211], v175 offset:35840
	ds_read_b128 v[212:215], v175 offset:36864
	ds_read_b128 v[216:219], v175 offset:37888
	ds_read_b128 v[220:223], v175 offset:38912
	ds_read_b128 v[224:227], v175 offset:39936
	global_load_lds_dwordx4 v146, s[36:37]
	s_mov_b32 m0, s42
	s_nop 0
	global_load_lds_dwordx4 v148, s[36:37]
	s_waitcnt vmcnt(8)
	s_waitcnt lgkmcnt(0)
	s_barrier
	s_setprio 1
	s_waitcnt lgkmcnt(0)
	v_mfma_i32_16x16x64_i8 v[142:145], v[106:109], v[196:199], v[142:145]
	v_mfma_i32_16x16x64_i8 v[138:141], v[122:125], v[196:199], v[138:141]
	v_mfma_i32_16x16x64_i8 v[118:121], v[106:109], v[204:207], v[118:121]
	v_mfma_i32_16x16x64_i8 v[114:117], v[122:125], v[204:207], v[114:117]
	v_mfma_i32_16x16x64_i8 v[94:97], v[106:109], v[212:215], v[94:97]
	v_mfma_i32_16x16x64_i8 v[90:93], v[122:125], v[212:215], v[90:93]
	v_mfma_i32_16x16x64_i8 v[78:81], v[106:109], v[220:223], v[78:81]
	v_mfma_i32_16x16x64_i8 v[74:77], v[122:125], v[220:223], v[74:77]
	v_mfma_i32_16x16x64_i8 v[142:145], v[110:113], v[200:203], v[142:145]
	v_mfma_i32_16x16x64_i8 v[138:141], v[126:129], v[200:203], v[138:141]
	v_mfma_i32_16x16x64_i8 v[118:121], v[110:113], v[208:211], v[118:121]
	v_mfma_i32_16x16x64_i8 v[114:117], v[126:129], v[208:211], v[114:117]
	v_mfma_i32_16x16x64_i8 v[94:97], v[110:113], v[216:219], v[94:97]
	v_mfma_i32_16x16x64_i8 v[90:93], v[126:129], v[216:219], v[90:93]
	v_mfma_i32_16x16x64_i8 v[78:81], v[110:113], v[224:227], v[78:81]
	v_mfma_i32_16x16x64_i8 v[74:77], v[126:129], v[224:227], v[74:77]
	s_setprio 0
	s_setprio 1
	v_mfma_i32_16x16x64_i8 v[134:137], v[176:179], v[196:199], v[134:137]
	v_mfma_i32_16x16x64_i8 v[130:133], v[188:191], v[196:199], v[130:133]
	v_mfma_i32_16x16x64_i8 v[102:105], v[176:179], v[204:207], v[102:105]
	v_mfma_i32_16x16x64_i8 v[98:101], v[188:191], v[204:207], v[98:101]
	v_mfma_i32_16x16x64_i8 v[86:89], v[176:179], v[212:215], v[86:89]
	v_mfma_i32_16x16x64_i8 v[82:85], v[188:191], v[212:215], v[82:85]
	v_mfma_i32_16x16x64_i8 v[70:73], v[176:179], v[220:223], v[70:73]
	v_mfma_i32_16x16x64_i8 v[66:69], v[188:191], v[220:223], v[66:69]
	v_mfma_i32_16x16x64_i8 v[134:137], v[184:187], v[200:203], v[134:137]
	v_mfma_i32_16x16x64_i8 v[130:133], v[192:195], v[200:203], v[130:133]
	v_mfma_i32_16x16x64_i8 v[102:105], v[184:187], v[208:211], v[102:105]
	v_mfma_i32_16x16x64_i8 v[98:101], v[192:195], v[208:211], v[98:101]
	v_mfma_i32_16x16x64_i8 v[86:89], v[184:187], v[216:219], v[86:89]
	v_mfma_i32_16x16x64_i8 v[82:85], v[192:195], v[216:219], v[82:85]
	v_mfma_i32_16x16x64_i8 v[70:73], v[184:187], v[224:227], v[70:73]
	v_mfma_i32_16x16x64_i8 v[66:69], v[192:195], v[224:227], v[66:69]
	s_setprio 0
	s_barrier
	s_add_u32 s98, s36, 0xfff80080
	s_addc_u32 s99, s37, -1
	s_add_i32 s36, s71, s39
	s_mov_b32 m0, s36
	ds_read_b128 v[196:199], v175 offset:49152
	ds_read_b128 v[200:203], v175 offset:50176
	ds_read_b128 v[204:207], v175 offset:51200
	ds_read_b128 v[208:211], v175 offset:52224
	ds_read_b128 v[212:215], v175 offset:53248
	ds_read_b128 v[216:219], v175 offset:54272
	ds_read_b128 v[220:223], v175 offset:55296
	ds_read_b128 v[224:227], v175 offset:56320
	s_add_u32 s100, s34, 0x80
	s_addc_u32 s101, s35, 0
	global_load_lds_dwordx4 v146, s[100:101]
	s_add_i32 m0, s36, 0x2000
	s_add_u32 s34, s34, 0x80080
	s_addc_u32 s35, s35, 0
	s_add_i32 s36, s72, s39
	global_load_lds_dwordx4 v148, s[100:101]
	s_mov_b32 m0, s36
	s_nop 0
	global_load_lds_dwordx4 v146, s[34:35]
	s_add_i32 m0, s36, 0x2000
	s_nop 0
	global_load_lds_dwordx4 v148, s[34:35]
	s_mov_b32 m0, s46
	s_nop 0
	global_load_lds_dwordx4 v146, s[98:99]
	s_mov_b32 m0, s47
	s_nop 0
	global_load_lds_dwordx4 v148, s[98:99]
	s_waitcnt vmcnt(8)
	s_waitcnt lgkmcnt(0)
	s_barrier
	s_setprio 1
	s_waitcnt lgkmcnt(0)
	v_mfma_i32_16x16x64_i8 v[62:65], v[106:109], v[196:199], v[62:65]
	v_mfma_i32_16x16x64_i8 v[58:61], v[122:125], v[196:199], v[58:61]
	v_mfma_i32_16x16x64_i8 v[46:49], v[106:109], v[204:207], v[46:49]
	v_mfma_i32_16x16x64_i8 v[42:45], v[122:125], v[204:207], v[42:45]
	v_mfma_i32_16x16x64_i8 v[30:33], v[106:109], v[212:215], v[30:33]
	v_mfma_i32_16x16x64_i8 v[26:29], v[122:125], v[212:215], v[26:29]
	v_mfma_i32_16x16x64_i8 v[14:17], v[106:109], v[220:223], v[14:17]
	v_mfma_i32_16x16x64_i8 v[10:13], v[122:125], v[220:223], v[10:13]
	v_mfma_i32_16x16x64_i8 v[62:65], v[110:113], v[200:203], v[62:65]
	v_mfma_i32_16x16x64_i8 v[58:61], v[126:129], v[200:203], v[58:61]
	v_mfma_i32_16x16x64_i8 v[46:49], v[110:113], v[208:211], v[46:49]
	v_mfma_i32_16x16x64_i8 v[42:45], v[126:129], v[208:211], v[42:45]
	v_mfma_i32_16x16x64_i8 v[30:33], v[110:113], v[216:219], v[30:33]
	v_mfma_i32_16x16x64_i8 v[26:29], v[126:129], v[216:219], v[26:29]
	v_mfma_i32_16x16x64_i8 v[14:17], v[110:113], v[224:227], v[14:17]
	v_mfma_i32_16x16x64_i8 v[10:13], v[126:129], v[224:227], v[10:13]
	s_setprio 0
	s_setprio 1
	v_mfma_i32_16x16x64_i8 v[54:57], v[176:179], v[196:199], v[54:57]
	v_mfma_i32_16x16x64_i8 v[50:53], v[188:191], v[196:199], v[50:53]
	v_mfma_i32_16x16x64_i8 v[38:41], v[176:179], v[204:207], v[38:41]
	v_mfma_i32_16x16x64_i8 v[34:37], v[188:191], v[204:207], v[34:37]
	v_mfma_i32_16x16x64_i8 v[22:25], v[176:179], v[212:215], v[22:25]
	v_mfma_i32_16x16x64_i8 v[18:21], v[188:191], v[212:215], v[18:21]
	v_mfma_i32_16x16x64_i8 v[6:9], v[176:179], v[220:223], v[6:9]
	v_mfma_i32_16x16x64_i8 v[2:5], v[188:191], v[220:223], v[2:5]
	v_mfma_i32_16x16x64_i8 v[54:57], v[184:187], v[200:203], v[54:57]
	v_mfma_i32_16x16x64_i8 v[50:53], v[192:195], v[200:203], v[50:53]
	v_mfma_i32_16x16x64_i8 v[38:41], v[184:187], v[208:211], v[38:41]
	v_mfma_i32_16x16x64_i8 v[34:37], v[192:195], v[208:211], v[34:37]
	v_mfma_i32_16x16x64_i8 v[22:25], v[184:187], v[216:219], v[22:25]
	v_mfma_i32_16x16x64_i8 v[18:21], v[192:195], v[216:219], v[18:21]
	v_mfma_i32_16x16x64_i8 v[6:9], v[184:187], v[224:227], v[6:9]
	v_mfma_i32_16x16x64_i8 v[2:5], v[192:195], v[224:227], v[2:5]
	s_setprio 0
	s_barrier
	s_add_i32 s70, s70, 2
	s_add_u32 s30, s30, 0x100
	s_addc_u32 s31, s31, 0
	s_add_u32 s68, s68, 0x100
	s_addc_u32 s69, s69, 0
	s_cmp_gt_u32 s70, 29

.LBB0_936:
	s_ashr_i32 s21, s20, 31
	s_lshl_b64 s[22:23], s[20:21], 23
	s_add_u32 s22, s48, s22
	s_addc_u32 s23, s49, s23
	s_and_b64 s[24:25], s[2:3], exec
	s_cselect_b32 s21, s23, s29
	s_cselect_b32 s66, s22, s28
	s_ashr_i32 s19, s18, 31
	s_lshl_b64 s[24:25], s[18:19], 23
	s_add_u32 s24, s44, s24
	s_addc_u32 s25, s45, s25
	s_and_b64 s[34:35], s[2:3], exec
	s_cselect_b32 s19, s25, s31
	s_cselect_b32 s67, s24, s30
	s_add_u32 s28, s28, 0x400080
	s_addc_u32 s29, s29, 0
	s_add_u32 s68, s30, 0x100
	s_addc_u32 s69, s31, 0
	s_mov_b32 s70, -2
	ds_read_b128 v[128:131], v159
	ds_read_b128 v[132:135], v159 offset:1024
	ds_read_b128 v[136:139], v159 offset:2048
	ds_read_b128 v[140:143], v159 offset:3072
	ds_read_b128 v[162:165], v160
	ds_read_b128 v[166:169], v160 offset:1024
	ds_read_b128 v[170:173], v160 offset:2048
	ds_read_b128 v[174:177], v160 offset:3072
	s_add_u32 s30, s28, 0xffc00080
	s_addc_u32 s31, s29, -1
	s_cmpk_eq_i32 s70, 0xfc
	s_cselect_b32 s35, s21, s31
	s_cselect_b32 s34, s66, s30
	s_cselect_b32 s31, s19, s69
	s_cselect_b32 s30, s67, s68
	s_add_i32 m0, s27, 0xc000
	ds_read_b128 v[178:181], v161
	ds_read_b128 v[184:187], v161 offset:1024
	ds_read_b128 v[188:191], v161 offset:2048
	ds_read_b128 v[192:195], v161 offset:3072
	ds_read_b128 v[196:199], v161 offset:4096
	ds_read_b128 v[200:203], v161 offset:5120
	ds_read_b128 v[204:207], v161 offset:6144
	ds_read_b128 v[208:211], v161 offset:7168
	global_load_lds_dwordx4 v148, s[28:29]
	s_add_i32 m0, s27, 0xe000
	s_nop 0
	global_load_lds_dwordx4 v150, s[28:29]
	s_cmp_lg_u32 s32, 0
	s_cbranch_scc1 .Lpw5a
	s_waitcnt vmcnt(8)
.Lpw5a:
	s_waitcnt lgkmcnt(0)
	s_barrier
	s_setprio 1
	s_waitcnt lgkmcnt(0)
	v_mfma_f32_16x16x32_bf16 v[124:127], v[128:131], v[178:181], 0
	v_mfma_f32_16x16x32_bf16 v[120:123], v[136:139], v[178:181], 0
	v_mfma_f32_16x16x32_bf16 v[116:119], v[128:131], v[188:191], 0
	v_mfma_f32_16x16x32_bf16 v[112:115], v[136:139], v[188:191], 0
	v_mfma_f32_16x16x32_bf16 v[108:111], v[128:131], v[196:199], 0
	v_mfma_f32_16x16x32_bf16 v[100:103], v[136:139], v[196:199], 0
	v_mfma_f32_16x16x32_bf16 v[76:79], v[128:131], v[204:207], 0
	v_mfma_f32_16x16x32_bf16 v[72:75], v[136:139], v[204:207], 0
	v_mfma_f32_16x16x32_bf16 v[124:127], v[132:135], v[184:187], v[124:127]
	v_mfma_f32_16x16x32_bf16 v[120:123], v[140:143], v[184:187], v[120:123]
	v_mfma_f32_16x16x32_bf16 v[116:119], v[132:135], v[192:195], v[116:119]
	v_mfma_f32_16x16x32_bf16 v[112:115], v[140:143], v[192:195], v[112:115]
	v_mfma_f32_16x16x32_bf16 v[108:111], v[132:135], v[200:203], v[108:111]
	v_mfma_f32_16x16x32_bf16 v[100:103], v[140:143], v[200:203], v[100:103]
	v_mfma_f32_16x16x32_bf16 v[76:79], v[132:135], v[208:211], v[76:79]
	v_mfma_f32_16x16x32_bf16 v[72:75], v[140:143], v[208:211], v[72:75]
	s_setprio 0
	s_setprio 1
	v_mfma_f32_16x16x32_bf16 v[104:107], v[162:165], v[178:181], 0
	v_mfma_f32_16x16x32_bf16 v[96:99], v[170:173], v[178:181], 0
	v_mfma_f32_16x16x32_bf16 v[92:95], v[162:165], v[188:191], 0
	v_mfma_f32_16x16x32_bf16 v[88:91], v[170:173], v[188:191], 0
	v_mfma_f32_16x16x32_bf16 v[84:87], v[162:165], v[196:199], 0
	v_mfma_f32_16x16x32_bf16 v[80:83], v[170:173], v[196:199], 0
	v_mfma_f32_16x16x32_bf16 v[68:71], v[162:165], v[204:207], 0
	v_mfma_f32_16x16x32_bf16 v[64:67], v[170:173], v[204:207], 0
	v_mfma_f32_16x16x32_bf16 v[104:107], v[166:169], v[184:187], v[104:107]
	v_mfma_f32_16x16x32_bf16 v[96:99], v[174:177], v[184:187], v[96:99]
	v_mfma_f32_16x16x32_bf16 v[92:95], v[166:169], v[192:195], v[92:95]
	v_mfma_f32_16x16x32_bf16 v[88:91], v[174:177], v[192:195], v[88:91]
	v_mfma_f32_16x16x32_bf16 v[84:87], v[166:169], v[200:203], v[84:87]
	v_mfma_f32_16x16x32_bf16 v[80:83], v[174:177], v[200:203], v[80:83]
	v_mfma_f32_16x16x32_bf16 v[68:71], v[166:169], v[208:211], v[68:71]
	v_mfma_f32_16x16x32_bf16 v[64:67], v[174:177], v[208:211], v[64:67]
	s_setprio 0
	s_barrier
	s_add_i32 s71, s51, s36
	s_mov_b32 m0, s71
	ds_read_b128 v[178:181], v161 offset:16384
	ds_read_b128 v[184:187], v161 offset:17408
	ds_read_b128 v[188:191], v161 offset:18432
	ds_read_b128 v[192:195], v161 offset:19456
	ds_read_b128 v[196:199], v161 offset:20480
	ds_read_b128 v[200:203], v161 offset:21504
	ds_read_b128 v[204:207], v161 offset:22528
	ds_read_b128 v[208:211], v161 offset:23552
	global_load_lds_dwordx4 v144, s[30:31]
	s_add_i32 m0, s71, 0x2000
	s_add_u32 s72, s30, 0x400000
	s_addc_u32 s73, s31, 0
	s_add_i32 s71, s52, s36
	global_load_lds_dwordx4 v146, s[30:31]
	s_mov_b32 m0, s71
	s_nop 0
	global_load_lds_dwordx4 v144, s[72:73]
	s_add_i32 m0, s71, 0x2000
	s_nop 0
	global_load_lds_dwordx4 v146, s[72:73]
	s_mov_b32 m0, s27
	s_nop 0
	global_load_lds_dwordx4 v144, s[34:35]
	s_mov_b32 m0, s38
	s_nop 0
	global_load_lds_dwordx4 v146, s[34:35]
	s_cmp_lg_u32 s32, 0
	s_cbranch_scc1 .Lpw5b
	s_waitcnt vmcnt(8)
.Lpw5b:
	s_mov_b32 s32, 1
	s_waitcnt lgkmcnt(0)
	s_barrier
	s_setprio 1
	s_waitcnt lgkmcnt(0)
	v_mfma_f32_16x16x32_bf16 v[60:63], v[128:131], v[178:181], 0
	v_mfma_f32_16x16x32_bf16 v[56:59], v[136:139], v[178:181], 0
	v_mfma_f32_16x16x32_bf16 v[52:55], v[128:131], v[188:191], 0
	v_mfma_f32_16x16x32_bf16 v[44:47], v[136:139], v[188:191], 0
	v_mfma_f32_16x16x32_bf16 v[36:39], v[128:131], v[196:199], 0
	v_mfma_f32_16x16x32_bf16 v[28:31], v[136:139], v[196:199], 0
	v_mfma_f32_16x16x32_bf16 v[20:23], v[128:131], v[204:207], 0
	v_mfma_f32_16x16x32_bf16 v[12:15], v[136:139], v[204:207], 0
	v_mfma_f32_16x16x32_bf16 v[60:63], v[132:135], v[184:187], v[60:63]
	v_mfma_f32_16x16x32_bf16 v[56:59], v[140:143], v[184:187], v[56:59]
	v_mfma_f32_16x16x32_bf16 v[52:55], v[132:135], v[192:195], v[52:55]
	v_mfma_f32_16x16x32_bf16 v[44:47], v[140:143], v[192:195], v[44:47]
	v_mfma_f32_16x16x32_bf16 v[36:39], v[132:135], v[200:203], v[36:39]
	v_mfma_f32_16x16x32_bf16 v[28:31], v[140:143], v[200:203], v[28:31]
	v_mfma_f32_16x16x32_bf16 v[20:23], v[132:135], v[208:211], v[20:23]
	v_mfma_f32_16x16x32_bf16 v[12:15], v[140:143], v[208:211], v[12:15]
	s_setprio 0
	s_setprio 1
	v_mfma_f32_16x16x32_bf16 v[48:51], v[162:165], v[178:181], 0
	v_mfma_f32_16x16x32_bf16 v[40:43], v[170:173], v[178:181], 0
	v_mfma_f32_16x16x32_bf16 v[32:35], v[162:165], v[188:191], 0
	v_mfma_f32_16x16x32_bf16 v[24:27], v[170:173], v[188:191], 0
	v_mfma_f32_16x16x32_bf16 v[16:19], v[162:165], v[196:199], 0
	v_mfma_f32_16x16x32_bf16 v[8:11], v[170:173], v[196:199], 0
	v_mfma_f32_16x16x32_bf16 v[4:7], v[162:165], v[204:207], 0
	v_mfma_f32_16x16x32_bf16 v[0:3], v[170:173], v[204:207], 0
	v_mfma_f32_16x16x32_bf16 v[48:51], v[166:169], v[184:187], v[48:51]
	v_mfma_f32_16x16x32_bf16 v[40:43], v[174:177], v[184:187], v[40:43]
	v_mfma_f32_16x16x32_bf16 v[32:35], v[166:169], v[192:195], v[32:35]
	v_mfma_f32_16x16x32_bf16 v[24:27], v[174:177], v[192:195], v[24:27]
	v_mfma_f32_16x16x32_bf16 v[16:19], v[166:169], v[200:203], v[16:19]
	v_mfma_f32_16x16x32_bf16 v[8:11], v[174:177], v[200:203], v[8:11]
	v_mfma_f32_16x16x32_bf16 v[4:7], v[166:169], v[208:211], v[4:7]
	v_mfma_f32_16x16x32_bf16 v[0:3], v[174:177], v[208:211], v[0:3]
	s_setprio 0
	s_barrier
	s_add_i32 s71, 0, 0x18000
	s_add_i32 s72, 0, 0x1c000
	v_add_u32_e32 v140, s71, v157
	v_add_u32_e32 v174, s72, v157
	ds_read_b128 v[128:131], v140
	ds_read_b128 v[132:135], v140 offset:1024
	ds_read_b128 v[136:139], v140 offset:2048
	ds_read_b128 v[140:143], v140 offset:3072
	ds_read_b128 v[162:165], v174
	ds_read_b128 v[166:169], v174 offset:1024
	ds_read_b128 v[170:173], v174 offset:2048
	ds_read_b128 v[174:177], v174 offset:3072
	s_add_u32 s34, s34, 0x400000
	s_addc_u32 s35, s35, 0
	s_mov_b32 m0, s39
	ds_read_b128 v[178:181], v161 offset:32768
	ds_read_b128 v[184:187], v161 offset:33792
	ds_read_b128 v[188:191], v161 offset:34816
	ds_read_b128 v[192:195], v161 offset:35840
	ds_read_b128 v[196:199], v161 offset:36864
	ds_read_b128 v[200:203], v161 offset:37888
	ds_read_b128 v[204:207], v161 offset:38912
	ds_read_b128 v[208:211], v161 offset:39936
	global_load_lds_dwordx4 v144, s[34:35]
	s_mov_b32 m0, s40
	s_nop 0
	global_load_lds_dwordx4 v146, s[34:35]
	s_waitcnt vmcnt(8)
	s_waitcnt lgkmcnt(0)
	s_barrier
	s_setprio 1
	s_waitcnt lgkmcnt(0)
	v_mfma_f32_16x16x32_bf16 v[124:127], v[128:131], v[178:181], v[124:127]
	v_mfma_f32_16x16x32_bf16 v[120:123], v[136:139], v[178:181], v[120:123]
	v_mfma_f32_16x16x32_bf16 v[116:119], v[128:131], v[188:191], v[116:119]
	v_mfma_f32_16x16x32_bf16 v[112:115], v[136:139], v[188:191], v[112:115]
	v_mfma_f32_16x16x32_bf16 v[108:111], v[128:131], v[196:199], v[108:111]
	v_mfma_f32_16x16x32_bf16 v[100:103], v[136:139], v[196:199], v[100:103]
	v_mfma_f32_16x16x32_bf16 v[76:79], v[128:131], v[204:207], v[76:79]
	v_mfma_f32_16x16x32_bf16 v[72:75], v[136:139], v[204:207], v[72:75]
	v_mfma_f32_16x16x32_bf16 v[124:127], v[132:135], v[184:187], v[124:127]
	v_mfma_f32_16x16x32_bf16 v[120:123], v[140:143], v[184:187], v[120:123]
	v_mfma_f32_16x16x32_bf16 v[116:119], v[132:135], v[192:195], v[116:119]
	v_mfma_f32_16x16x32_bf16 v[112:115], v[140:143], v[192:195], v[112:115]
	v_mfma_f32_16x16x32_bf16 v[108:111], v[132:135], v[200:203], v[108:111]
	v_mfma_f32_16x16x32_bf16 v[100:103], v[140:143], v[200:203], v[100:103]
	v_mfma_f32_16x16x32_bf16 v[76:79], v[132:135], v[208:211], v[76:79]
	v_mfma_f32_16x16x32_bf16 v[72:75], v[140:143], v[208:211], v[72:75]
	s_setprio 0
	s_setprio 1
	v_mfma_f32_16x16x32_bf16 v[104:107], v[162:165], v[178:181], v[104:107]
	v_mfma_f32_16x16x32_bf16 v[96:99], v[170:173], v[178:181], v[96:99]
	v_mfma_f32_16x16x32_bf16 v[92:95], v[162:165], v[188:191], v[92:95]
	v_mfma_f32_16x16x32_bf16 v[88:91], v[170:173], v[188:191], v[88:91]
	v_mfma_f32_16x16x32_bf16 v[84:87], v[162:165], v[196:199], v[84:87]
	v_mfma_f32_16x16x32_bf16 v[80:83], v[170:173], v[196:199], v[80:83]
	v_mfma_f32_16x16x32_bf16 v[68:71], v[162:165], v[204:207], v[68:71]
	v_mfma_f32_16x16x32_bf16 v[64:67], v[170:173], v[204:207], v[64:67]
	v_mfma_f32_16x16x32_bf16 v[104:107], v[166:169], v[184:187], v[104:107]
	v_mfma_f32_16x16x32_bf16 v[96:99], v[174:177], v[184:187], v[96:99]
	v_mfma_f32_16x16x32_bf16 v[92:95], v[166:169], v[192:195], v[92:95]
	v_mfma_f32_16x16x32_bf16 v[88:91], v[174:177], v[192:195], v[88:91]
	v_mfma_f32_16x16x32_bf16 v[84:87], v[166:169], v[200:203], v[84:87]
	v_mfma_f32_16x16x32_bf16 v[80:83], v[174:177], v[200:203], v[80:83]
	v_mfma_f32_16x16x32_bf16 v[68:71], v[166:169], v[208:211], v[68:71]
	v_mfma_f32_16x16x32_bf16 v[64:67], v[174:177], v[208:211], v[64:67]
	s_setprio 0
	s_barrier
	s_add_u32 s98, s34, 0xffc00080
	s_addc_u32 s99, s35, -1
	s_add_i32 s34, s71, s36
	s_mov_b32 m0, s34
	ds_read_b128 v[178:181], v161 offset:49152
	ds_read_b128 v[184:187], v161 offset:50176
	ds_read_b128 v[188:191], v161 offset:51200
	ds_read_b128 v[192:195], v161 offset:52224
	ds_read_b128 v[196:199], v161 offset:53248
	ds_read_b128 v[200:203], v161 offset:54272
	ds_read_b128 v[204:207], v161 offset:55296
	ds_read_b128 v[208:211], v161 offset:56320
	s_add_u32 s100, s30, 0x80
	s_addc_u32 s101, s31, 0
	global_load_lds_dwordx4 v144, s[100:101]
	s_add_i32 m0, s34, 0x2000
	s_add_u32 s30, s30, 0x400080
	s_addc_u32 s31, s31, 0
	s_add_i32 s34, s72, s36
	global_load_lds_dwordx4 v146, s[100:101]
	s_mov_b32 m0, s34
	s_nop 0
	global_load_lds_dwordx4 v144, s[30:31]
	s_add_i32 m0, s34, 0x2000
	s_nop 0
	global_load_lds_dwordx4 v146, s[30:31]
	s_mov_b32 m0, s47
	s_nop 0
	global_load_lds_dwordx4 v144, s[98:99]
	s_mov_b32 m0, s50
	s_nop 0
	global_load_lds_dwordx4 v146, s[98:99]
	s_waitcnt vmcnt(8)
	s_waitcnt lgkmcnt(0)
	s_barrier
	s_setprio 1
	s_waitcnt lgkmcnt(0)
	v_mfma_f32_16x16x32_bf16 v[60:63], v[128:131], v[178:181], v[60:63]
	v_mfma_f32_16x16x32_bf16 v[56:59], v[136:139], v[178:181], v[56:59]
	v_mfma_f32_16x16x32_bf16 v[52:55], v[128:131], v[188:191], v[52:55]
	v_mfma_f32_16x16x32_bf16 v[44:47], v[136:139], v[188:191], v[44:47]
	v_mfma_f32_16x16x32_bf16 v[36:39], v[128:131], v[196:199], v[36:39]
	v_mfma_f32_16x16x32_bf16 v[28:31], v[136:139], v[196:199], v[28:31]
	v_mfma_f32_16x16x32_bf16 v[20:23], v[128:131], v[204:207], v[20:23]
	v_mfma_f32_16x16x32_bf16 v[12:15], v[136:139], v[204:207], v[12:15]
	v_mfma_f32_16x16x32_bf16 v[60:63], v[132:135], v[184:187], v[60:63]
	v_mfma_f32_16x16x32_bf16 v[56:59], v[140:143], v[184:187], v[56:59]
	v_mfma_f32_16x16x32_bf16 v[52:55], v[132:135], v[192:195], v[52:55]
	v_mfma_f32_16x16x32_bf16 v[44:47], v[140:143], v[192:195], v[44:47]
	v_mfma_f32_16x16x32_bf16 v[36:39], v[132:135], v[200:203], v[36:39]
	v_mfma_f32_16x16x32_bf16 v[28:31], v[140:143], v[200:203], v[28:31]
	v_mfma_f32_16x16x32_bf16 v[20:23], v[132:135], v[208:211], v[20:23]
	v_mfma_f32_16x16x32_bf16 v[12:15], v[140:143], v[208:211], v[12:15]
	s_setprio 0
	s_setprio 1
	v_mfma_f32_16x16x32_bf16 v[48:51], v[162:165], v[178:181], v[48:51]
	v_mfma_f32_16x16x32_bf16 v[40:43], v[170:173], v[178:181], v[40:43]
	v_mfma_f32_16x16x32_bf16 v[32:35], v[162:165], v[188:191], v[32:35]
	v_mfma_f32_16x16x32_bf16 v[24:27], v[170:173], v[188:191], v[24:27]
	v_mfma_f32_16x16x32_bf16 v[16:19], v[162:165], v[196:199], v[16:19]
	v_mfma_f32_16x16x32_bf16 v[8:11], v[170:173], v[196:199], v[8:11]
	v_mfma_f32_16x16x32_bf16 v[4:7], v[162:165], v[204:207], v[4:7]
	v_mfma_f32_16x16x32_bf16 v[0:3], v[170:173], v[204:207], v[0:3]
	v_mfma_f32_16x16x32_bf16 v[48:51], v[166:169], v[184:187], v[48:51]
	v_mfma_f32_16x16x32_bf16 v[40:43], v[174:177], v[184:187], v[40:43]
	v_mfma_f32_16x16x32_bf16 v[32:35], v[166:169], v[192:195], v[32:35]
	v_mfma_f32_16x16x32_bf16 v[24:27], v[174:177], v[192:195], v[24:27]
	v_mfma_f32_16x16x32_bf16 v[16:19], v[166:169], v[200:203], v[16:19]
	v_mfma_f32_16x16x32_bf16 v[8:11], v[174:177], v[200:203], v[8:11]
	v_mfma_f32_16x16x32_bf16 v[4:7], v[166:169], v[208:211], v[4:7]
	v_mfma_f32_16x16x32_bf16 v[0:3], v[174:177], v[208:211], v[0:3]
	s_setprio 0
	s_barrier
	s_add_i32 s70, s70, 2
	s_add_u32 s28, s28, 0x100
	s_addc_u32 s29, s29, 0
	s_add_u32 s68, s68, 0x100
	s_addc_u32 s69, s69, 0
	s_cmpk_gt_u32 s70, 0xfd
